# GEMM K-loops: also removed the 24 duplicate s_waitcnt lgkmcnt(0) that directly followed the inline-asm wait
# baseline (speedup 1.0000x reference)
; #define PG8_STAGE(bufoff, gbase, voff) do { _Pragma("unroll") for (int _i = 0; _i < 2; ++_i) \
;         __builtin_amdgcn_global_load_lds((const unsigned*)((const char*)(gbase) + (voff)[_i]), (LAS unsigned*)(lds + (bufoff) + ldsw + _i * 8192), 16, 0, 0); } while (0)
; #define PG8_LDA(dst, b, h) do { _Pragma("unroll") for (int m = 0; m < 4; ++m) _Pragma("unroll") for (int k = 0; k < 2; ++k) dst[m][k] = *(const LAS bf16x8*)(lds + PG8_SA(b, h) + aoff + m * 2048 + k * 1024); } while (0)
; #define PG8_LDB(dst, b, h) do { _Pragma("unroll") for (int n = 0; n < 2; ++n) _Pragma("unroll") for (int k = 0; k < 2; ++k) dst[n][k] = *(const LAS bf16x8*)(lds + PG8_SB(b, h) + boff + n * 2048 + k * 1024); } while (0)
; #define PG8_MMA(ai, bj, At, Bt) do { __builtin_amdgcn_s_setprio(1); _Pragma("unroll") for (int m = 0; m < 4; ++m) _Pragma("unroll") for (int n = 0; n < 2; ++n) _Pragma("unroll") for (int k = 0; k < 2; ++k) \
;         acc[ai][bj][m][n] = __builtin_amdgcn_mfma_f32_16x16x32_bf16(Bt[n][k], At[m][k], acc[ai][bj][m][n], 0, 0, 0); __builtin_amdgcn_s_setprio(0); } while (0)
; #define PG8_WAIT_L(n) asm volatile("s_waitcnt lgkmcnt(" #n ")" ::: "memory")
; #define PG8_BAR __builtin_amdgcn_s_barrier()
; #define PG8_SCHED __builtin_amdgcn_sched_barrier(0)
; template <class Epi, bool SEG>
; __device__ __forceinline__ void gemm_phase(LAS unsigned char* lds, const Gemm g, const StaticOrder& S, const Epi& E) {
;     ...
;         for (int t = 0; t < nt; t += 2) {
;             const bool last = (t == nt - 2);
;             const char* a1 = cA + akoff<SEG>(t) + kstep;
;             const char* a2 = last ? nA : cA + akoff<SEG>(t + 2); const char* b2 = last ? nB : cB + (size_t)(t + 2) * kstep;
;             const char* a3 = a2 + kstep; const char* b3 = b2 + kstep;
;             PG8_LDB(B0, 0, 0); PG8_SCHED; PG8_LDA(At, 0, 0); PG8_STAGE(PG8_SA(1, 1), a1 + hstepA, voffA);
;             PG8_WAIT_L(8); PG8_BAR; PG8_WAIT_L(0); PG8_MMA(0, 0, At, B0); PG8_BAR; PG8_SCHED;
;             PG8_LDB(B1, 0, 1); PG8_STAGE(PG8_SB(0, 0), b2, voffB);
;             PG8_BAR; PG8_WAIT_L(0); PG8_MMA(0, 1, At, B1); PG8_BAR;
;             PG8_LDA(At, 0, 1); PG8_STAGE(PG8_SA(0, 0), a2, voffA);
;             PG8_BAR; PG8_WAIT_L(0); PG8_MMA(1, 0, At, B0); PG8_BAR; PG8_SCHED;
.LBB0_47:
	s_add_u32 s14, s12, 0xffe00080
	s_addc_u32 s15, s13, -1
	s_add_i32 s39, 0, 0x10000
	v_add_u32_e32 v152, s39, v155
	ds_read_b128 v[180:183], v152
	ds_read_b128 v[184:187], v152 offset:1024
	ds_read_b128 v[188:191], v152 offset:2048
	ds_read_b128 v[198:201], v152 offset:3072
	s_cmpk_eq_i32 s38, 0x7c
	s_cselect_b32 s17, s5, s15
	s_cselect_b32 s16, s34, s14
	s_cselect_b32 s15, s1, s37
	s_cselect_b32 s14, s35, s36
	v_lshl_add_u64 v[152:153], s[12:13], 0, v[148:149]
	s_add_i32 m0, s9, 0xc000
	ds_read_b128 v[202:205], v157
	ds_read_b128 v[206:209], v157 offset:1024
	ds_read_b128 v[210:213], v157 offset:2048
	ds_read_b128 v[214:217], v157 offset:3072
	ds_read_b128 v[218:221], v157 offset:4096
	ds_read_b128 v[222:225], v157 offset:5120
	ds_read_b128 v[226:229], v157 offset:6144
	ds_read_b128 v[230:233], v157 offset:7168
	global_load_lds_dwordx4 v[152:153], off
	v_lshl_add_u64 v[152:153], s[12:13], 0, v[150:151]
	s_add_i32 m0, s9, 0xe000
	s_nop 0
	global_load_lds_dwordx4 v[152:153], off
	s_waitcnt lgkmcnt(8)
	s_barrier
	s_waitcnt lgkmcnt(0)
	v_mfma_f32_16x16x32_bf16 v[126:129], v[180:183], v[202:205], v[126:129]
	v_mfma_f32_16x16x32_bf16 v[122:125], v[188:191], v[202:205], v[122:125]
	v_mfma_f32_16x16x32_bf16 v[118:121], v[180:183], v[210:213], v[118:121]
	v_mfma_f32_16x16x32_bf16 v[110:113], v[188:191], v[210:213], v[110:113]
	v_mfma_f32_16x16x32_bf16 v[102:105], v[180:183], v[218:221], v[102:105]
	v_mfma_f32_16x16x32_bf16 v[94:97], v[188:191], v[218:221], v[94:97]
	v_mfma_f32_16x16x32_bf16 v[82:85], v[180:183], v[226:229], v[82:85]
	v_mfma_f32_16x16x32_bf16 v[74:77], v[188:191], v[226:229], v[74:77]
	v_mfma_f32_16x16x32_bf16 v[126:129], v[184:187], v[206:209], v[126:129]
	v_mfma_f32_16x16x32_bf16 v[122:125], v[198:201], v[206:209], v[122:125]
	v_mfma_f32_16x16x32_bf16 v[118:121], v[184:187], v[214:217], v[118:121]
	v_mfma_f32_16x16x32_bf16 v[110:113], v[198:201], v[214:217], v[110:113]
	v_mfma_f32_16x16x32_bf16 v[102:105], v[184:187], v[222:225], v[102:105]
	v_mfma_f32_16x16x32_bf16 v[94:97], v[198:201], v[222:225], v[94:97]
	v_mfma_f32_16x16x32_bf16 v[82:85], v[184:187], v[230:233], v[82:85]
	v_mfma_f32_16x16x32_bf16 v[74:77], v[198:201], v[230:233], v[74:77]
	s_barrier
	s_add_i32 s42, 0, 0x14000
	v_add_u32_e32 v152, s42, v155
	s_add_i32 s39, s39, s23
	ds_read_b128 v[234:237], v152
	ds_read_b128 v[238:241], v152 offset:1024
	ds_read_b128 v[242:245], v152 offset:2048
	ds_read_b128 v[246:249], v152 offset:3072
	v_lshl_add_u64 v[152:153], s[14:15], 0, v[0:1]
	s_mov_b32 m0, s39
	v_lshl_add_u64 v[158:159], s[14:15], 0, v[142:143]
	global_load_lds_dwordx4 v[152:153], off
	s_add_i32 m0, s39, 0x2000
	s_nop 0
	global_load_lds_dwordx4 v[158:159], off
	s_barrier
	s_waitcnt lgkmcnt(0)
	v_mfma_f32_16x16x32_bf16 v[114:117], v[234:237], v[202:205], v[114:117]
	v_mfma_f32_16x16x32_bf16 v[106:109], v[242:245], v[202:205], v[106:109]
	v_mfma_f32_16x16x32_bf16 v[98:101], v[234:237], v[210:213], v[98:101]
	v_mfma_f32_16x16x32_bf16 v[90:93], v[242:245], v[210:213], v[90:93]
	v_mfma_f32_16x16x32_bf16 v[86:89], v[234:237], v[218:221], v[86:89]
	v_mfma_f32_16x16x32_bf16 v[78:81], v[242:245], v[218:221], v[78:81]
	v_mfma_f32_16x16x32_bf16 v[70:73], v[234:237], v[226:229], v[70:73]
	v_mfma_f32_16x16x32_bf16 v[66:69], v[242:245], v[226:229], v[66:69]
	v_mfma_f32_16x16x32_bf16 v[114:117], v[238:241], v[206:209], v[114:117]
	v_mfma_f32_16x16x32_bf16 v[106:109], v[246:249], v[206:209], v[106:109]
	v_mfma_f32_16x16x32_bf16 v[98:101], v[238:241], v[214:217], v[98:101]
	v_mfma_f32_16x16x32_bf16 v[90:93], v[246:249], v[214:217], v[90:93]
	v_mfma_f32_16x16x32_bf16 v[86:89], v[238:241], v[222:225], v[86:89]
	v_mfma_f32_16x16x32_bf16 v[78:81], v[246:249], v[222:225], v[78:81]
	v_mfma_f32_16x16x32_bf16 v[70:73], v[238:241], v[230:233], v[70:73]
	v_mfma_f32_16x16x32_bf16 v[66:69], v[246:249], v[230:233], v[66:69]
	s_mov_b32 m0, s9
	v_lshl_add_u64 v[192:193], s[16:17], 0, v[146:147]
	s_barrier
	ds_read_b128 v[202:205], v157 offset:16384
	ds_read_b128 v[206:209], v157 offset:17408
	ds_read_b128 v[210:213], v157 offset:18432
	ds_read_b128 v[214:217], v157 offset:19456
	ds_read_b128 v[218:221], v157 offset:20480
	ds_read_b128 v[222:225], v157 offset:21504
	ds_read_b128 v[226:229], v157 offset:22528
	ds_read_b128 v[230:233], v157 offset:23552
	global_load_lds_dwordx4 v[192:193], off
	v_lshl_add_u64 v[250:251], s[16:17], 0, v[144:145]
	s_mov_b32 m0, s25
	s_nop 0
	global_load_lds_dwordx4 v[250:251], off
	s_barrier
	s_waitcnt lgkmcnt(0)
	v_mfma_f32_16x16x32_bf16 v[62:65], v[180:183], v[202:205], v[62:65]
	v_mfma_f32_16x16x32_bf16 v[58:61], v[188:191], v[202:205], v[58:61]
	v_mfma_f32_16x16x32_bf16 v[54:57], v[180:183], v[210:213], v[54:57]
	v_mfma_f32_16x16x32_bf16 v[46:49], v[188:191], v[210:213], v[46:49]
	v_mfma_f32_16x16x32_bf16 v[38:41], v[180:183], v[218:221], v[38:41]
	v_mfma_f32_16x16x32_bf16 v[30:33], v[188:191], v[218:221], v[30:33]
	v_mfma_f32_16x16x32_bf16 v[22:25], v[180:183], v[226:229], v[22:25]
	v_mfma_f32_16x16x32_bf16 v[14:17], v[188:191], v[226:229], v[14:17]
	v_mfma_f32_16x16x32_bf16 v[62:65], v[184:187], v[206:209], v[62:65]
	v_mfma_f32_16x16x32_bf16 v[58:61], v[198:201], v[206:209], v[58:61]
	v_mfma_f32_16x16x32_bf16 v[54:57], v[184:187], v[214:217], v[54:57]
	v_mfma_f32_16x16x32_bf16 v[46:49], v[198:201], v[214:217], v[46:49]
	v_mfma_f32_16x16x32_bf16 v[38:41], v[184:187], v[222:225], v[38:41]
	v_mfma_f32_16x16x32_bf16 v[30:33], v[198:201], v[222:225], v[30:33]
	v_mfma_f32_16x16x32_bf16 v[22:25], v[184:187], v[230:233], v[22:25]
	v_mfma_f32_16x16x32_bf16 v[14:17], v[198:201], v[230:233], v[14:17]
	s_barrier
; #define PG8_STAGE(bufoff, gbase, voff) do { _Pragma("unroll") for (int _i = 0; _i < 2; ++_i) \
;         __builtin_amdgcn_global_load_lds((const unsigned*)((const char*)(gbase) + (voff)[_i]), (LAS unsigned*)(lds + (bufoff) + ldsw + _i * 8192), 16, 0, 0); } while (0)
; #define PG8_LDA(dst, b, h) do { _Pragma("unroll") for (int m = 0; m < 4; ++m) _Pragma("unroll") for (int k = 0; k < 2; ++k) dst[m][k] = *(const LAS bf16x8*)(lds + PG8_SA(b, h) + aoff + m * 2048 + k * 1024); } while (0)
; #define PG8_LDB(dst, b, h) do { _Pragma("unroll") for (int n = 0; n < 2; ++n) _Pragma("unroll") for (int k = 0; k < 2; ++k) dst[n][k] = *(const LAS bf16x8*)(lds + PG8_SB(b, h) + boff + n * 2048 + k * 1024); } while (0)
; #define PG8_MMA(ai, bj, At, Bt) do { __builtin_amdgcn_s_setprio(1); _Pragma("unroll") for (int m = 0; m < 4; ++m) _Pragma("unroll") for (int n = 0; n < 2; ++n) _Pragma("unroll") for (int k = 0; k < 2; ++k) \
;         acc[ai][bj][m][n] = __builtin_amdgcn_mfma_f32_16x16x32_bf16(Bt[n][k], At[m][k], acc[ai][bj][m][n], 0, 0, 0); __builtin_amdgcn_s_setprio(0); } while (0)
; #define PG8_WAIT_V(n) asm volatile("s_waitcnt vmcnt(" #n ")" ::: "memory")
; #define PG8_WAIT_L(n) asm volatile("s_waitcnt lgkmcnt(" #n ")" ::: "memory")
; #define PG8_BAR __builtin_amdgcn_s_barrier()
; #define PG8_SCHED __builtin_amdgcn_sched_barrier(0)
; template <class Epi, bool SEG>
; __device__ __forceinline__ void gemm_phase(LAS unsigned char* lds, const Gemm g, const StaticOrder& S, const Epi& E) {
;     ...
;             PG8_STAGE(PG8_SB(0, 1), b2 + hstepB, voffB);
;             PG8_WAIT_V(6); PG8_BAR; PG8_MMA(1, 1, At, B1); PG8_BAR;
;             PG8_LDB(B0, 1, 0); PG8_SCHED; PG8_LDA(At, 1, 0); PG8_STAGE(PG8_SA(0, 1), a2 + hstepA, voffA);
;             PG8_WAIT_L(8); PG8_BAR; PG8_WAIT_L(0); PG8_MMA(0, 0, At, B0); PG8_BAR; PG8_SCHED;
;             PG8_LDB(B1, 1, 1); PG8_STAGE(PG8_SB(1, 0), b3, voffB);
;             PG8_BAR; PG8_WAIT_L(0); PG8_MMA(0, 1, At, B1); PG8_BAR;
;             PG8_LDA(At, 1, 1); PG8_STAGE(PG8_SA(1, 0), a3, voffA);
;             PG8_BAR; PG8_WAIT_L(0); PG8_MMA(1, 0, At, B0); PG8_BAR; PG8_SCHED;
	s_add_u32 s40, s14, 0x200000
	s_addc_u32 s41, s15, 0
	s_add_i32 s39, s42, s23
	v_lshl_add_u64 v[180:181], s[40:41], 0, v[0:1]
	s_mov_b32 m0, s39
	s_nop 0
	global_load_lds_dwordx4 v[180:181], off
	v_lshl_add_u64 v[180:181], s[40:41], 0, v[142:143]
	s_add_i32 m0, s39, 0x2000
	s_nop 0
	global_load_lds_dwordx4 v[180:181], off
	s_waitcnt vmcnt(6)
	s_barrier
	v_mfma_f32_16x16x32_bf16 v[50:53], v[234:237], v[202:205], v[50:53]
	v_mfma_f32_16x16x32_bf16 v[42:45], v[242:245], v[202:205], v[42:45]
	v_mfma_f32_16x16x32_bf16 v[34:37], v[234:237], v[210:213], v[34:37]
	v_mfma_f32_16x16x32_bf16 v[26:29], v[242:245], v[210:213], v[26:29]
	v_mfma_f32_16x16x32_bf16 v[18:21], v[234:237], v[218:221], v[18:21]
	v_mfma_f32_16x16x32_bf16 v[10:13], v[242:245], v[218:221], v[10:13]
	v_mfma_f32_16x16x32_bf16 v[6:9], v[234:237], v[226:229], v[6:9]
	v_mfma_f32_16x16x32_bf16 v[2:5], v[242:245], v[226:229], v[2:5]
	v_mfma_f32_16x16x32_bf16 v[50:53], v[238:241], v[206:209], v[50:53]
	v_mfma_f32_16x16x32_bf16 v[42:45], v[246:249], v[206:209], v[42:45]
	v_mfma_f32_16x16x32_bf16 v[34:37], v[238:241], v[214:217], v[34:37]
	v_mfma_f32_16x16x32_bf16 v[26:29], v[246:249], v[214:217], v[26:29]
	v_mfma_f32_16x16x32_bf16 v[18:21], v[238:241], v[222:225], v[18:21]
	v_mfma_f32_16x16x32_bf16 v[10:13], v[246:249], v[222:225], v[10:13]
	v_mfma_f32_16x16x32_bf16 v[6:9], v[238:241], v[230:233], v[6:9]
	v_mfma_f32_16x16x32_bf16 v[2:5], v[246:249], v[230:233], v[2:5]
	s_add_i32 s39, 0, 0x18000
	v_add_u32_e32 v179, s39, v155
	s_barrier
	ds_read_b128 v[180:183], v179
	ds_read_b128 v[184:187], v179 offset:1024
	ds_read_b128 v[188:191], v179 offset:2048
	ds_read_b128 v[198:201], v179 offset:3072
	s_add_u32 s16, s16, 0x200000
	s_addc_u32 s17, s17, 0
	s_mov_b32 m0, s26
	v_lshl_add_u64 v[234:235], s[16:17], 0, v[146:147]
	ds_read_b128 v[202:205], v157 offset:32768
	ds_read_b128 v[206:209], v157 offset:33792
	ds_read_b128 v[210:213], v157 offset:34816
	ds_read_b128 v[214:217], v157 offset:35840
	ds_read_b128 v[218:221], v157 offset:36864
	ds_read_b128 v[222:225], v157 offset:37888
	ds_read_b128 v[226:229], v157 offset:38912
	ds_read_b128 v[230:233], v157 offset:39936
	global_load_lds_dwordx4 v[234:235], off
	v_lshl_add_u64 v[234:235], s[16:17], 0, v[144:145]
	s_mov_b32 m0, s27
	s_nop 0
	global_load_lds_dwordx4 v[234:235], off
	s_waitcnt lgkmcnt(8)
	s_barrier
	s_waitcnt lgkmcnt(0)
	v_mfma_f32_16x16x32_bf16 v[126:129], v[180:183], v[202:205], v[126:129]
	v_mfma_f32_16x16x32_bf16 v[122:125], v[188:191], v[202:205], v[122:125]
	v_mfma_f32_16x16x32_bf16 v[118:121], v[180:183], v[210:213], v[118:121]
	v_mfma_f32_16x16x32_bf16 v[110:113], v[188:191], v[210:213], v[110:113]
	v_mfma_f32_16x16x32_bf16 v[102:105], v[180:183], v[218:221], v[102:105]
	v_mfma_f32_16x16x32_bf16 v[94:97], v[188:191], v[218:221], v[94:97]
	v_mfma_f32_16x16x32_bf16 v[82:85], v[180:183], v[226:229], v[82:85]
	v_mfma_f32_16x16x32_bf16 v[74:77], v[188:191], v[226:229], v[74:77]
	v_mfma_f32_16x16x32_bf16 v[126:129], v[184:187], v[206:209], v[126:129]
	v_mfma_f32_16x16x32_bf16 v[122:125], v[198:201], v[206:209], v[122:125]
	v_mfma_f32_16x16x32_bf16 v[118:121], v[184:187], v[214:217], v[118:121]
	v_mfma_f32_16x16x32_bf16 v[110:113], v[198:201], v[214:217], v[110:113]
	v_mfma_f32_16x16x32_bf16 v[102:105], v[184:187], v[222:225], v[102:105]
	v_mfma_f32_16x16x32_bf16 v[94:97], v[198:201], v[222:225], v[94:97]
	v_mfma_f32_16x16x32_bf16 v[82:85], v[184:187], v[230:233], v[82:85]
	v_mfma_f32_16x16x32_bf16 v[74:77], v[198:201], v[230:233], v[74:77]
	s_barrier
	s_add_i32 s16, 0, 0x1c000
	s_add_i32 s17, s39, s23
	v_add_u32_e32 v179, s16, v155
	v_lshl_add_u64 v[152:153], v[152:153], 0, s[96:97]
	s_mov_b32 m0, s17
	ds_read_b128 v[234:237], v179
	ds_read_b128 v[238:241], v179 offset:1024
	ds_read_b128 v[242:245], v179 offset:2048
	ds_read_b128 v[246:249], v179 offset:3072
	global_load_lds_dwordx4 v[152:153], off
	v_lshl_add_u64 v[152:153], v[158:159], 0, s[96:97]
	s_add_i32 m0, s17, 0x2000
	s_nop 0
	global_load_lds_dwordx4 v[152:153], off
	s_barrier
	s_waitcnt lgkmcnt(0)
	v_mfma_f32_16x16x32_bf16 v[114:117], v[234:237], v[202:205], v[114:117]
	v_mfma_f32_16x16x32_bf16 v[106:109], v[242:245], v[202:205], v[106:109]
	v_mfma_f32_16x16x32_bf16 v[98:101], v[234:237], v[210:213], v[98:101]
	v_mfma_f32_16x16x32_bf16 v[90:93], v[242:245], v[210:213], v[90:93]
	v_mfma_f32_16x16x32_bf16 v[86:89], v[234:237], v[218:221], v[86:89]
	v_mfma_f32_16x16x32_bf16 v[78:81], v[242:245], v[218:221], v[78:81]
	v_mfma_f32_16x16x32_bf16 v[70:73], v[234:237], v[226:229], v[70:73]
	v_mfma_f32_16x16x32_bf16 v[66:69], v[242:245], v[226:229], v[66:69]
	v_mfma_f32_16x16x32_bf16 v[114:117], v[238:241], v[206:209], v[114:117]
	v_mfma_f32_16x16x32_bf16 v[106:109], v[246:249], v[206:209], v[106:109]
	v_mfma_f32_16x16x32_bf16 v[98:101], v[238:241], v[214:217], v[98:101]
	v_mfma_f32_16x16x32_bf16 v[90:93], v[246:249], v[214:217], v[90:93]
	v_mfma_f32_16x16x32_bf16 v[86:89], v[238:241], v[222:225], v[86:89]
	v_mfma_f32_16x16x32_bf16 v[78:81], v[246:249], v[222:225], v[78:81]
	v_mfma_f32_16x16x32_bf16 v[70:73], v[238:241], v[230:233], v[70:73]
	v_mfma_f32_16x16x32_bf16 v[66:69], v[246:249], v[230:233], v[66:69]
	s_mov_b32 m0, s28
	v_lshl_add_u64 v[152:153], v[192:193], 0, s[96:97]
	s_barrier
	ds_read_b128 v[202:205], v157 offset:49152
	ds_read_b128 v[206:209], v157 offset:50176
	ds_read_b128 v[210:213], v157 offset:51200
	ds_read_b128 v[214:217], v157 offset:52224
	ds_read_b128 v[218:221], v157 offset:53248
	ds_read_b128 v[222:225], v157 offset:54272
	ds_read_b128 v[226:229], v157 offset:55296
	ds_read_b128 v[230:233], v157 offset:56320
	global_load_lds_dwordx4 v[152:153], off
	v_lshl_add_u64 v[152:153], v[250:251], 0, s[96:97]
	s_mov_b32 m0, s29
	s_nop 0
	global_load_lds_dwordx4 v[152:153], off
	s_barrier
; #define PG8_STAGE(bufoff, gbase, voff) do { _Pragma("unroll") for (int _i = 0; _i < 2; ++_i) \
;         __builtin_amdgcn_global_load_lds((const unsigned*)((const char*)(gbase) + (voff)[_i]), (LAS unsigned*)(lds + (bufoff) + ldsw + _i * 8192), 16, 0, 0); } while (0)
; #define PG8_LDA(dst, b, h) do { _Pragma("unroll") for (int m = 0; m < 4; ++m) _Pragma("unroll") for (int k = 0; k < 2; ++k) dst[m][k] = *(const LAS bf16x8*)(lds + PG8_SA(b, h) + aoff + m * 2048 + k * 1024); } while (0)
; #define PG8_MMA(ai, bj, At, Bt) do { __builtin_amdgcn_s_setprio(1); _Pragma("unroll") for (int m = 0; m < 4; ++m) _Pragma("unroll") for (int n = 0; n < 2; ++n) _Pragma("unroll") for (int k = 0; k < 2; ++k) \
;         acc[ai][bj][m][n] = __builtin_amdgcn_mfma_f32_16x16x32_bf16(Bt[n][k], At[m][k], acc[ai][bj][m][n], 0, 0, 0); __builtin_amdgcn_s_setprio(0); } while (0)
; #define PG8_WAIT_V(n) asm volatile("s_waitcnt vmcnt(" #n ")" ::: "memory")
; #define PG8_WAIT_L(n) asm volatile("s_waitcnt lgkmcnt(" #n ")" ::: "memory")
; #define PG8_BAR __builtin_amdgcn_s_barrier()
; #define PG8_SCHED __builtin_amdgcn_sched_barrier(0)
; template <class Epi, bool SEG>
; __device__ __forceinline__ void gemm_phase(LAS unsigned char* lds, const Gemm g, const StaticOrder& S, const Epi& E) {
;     ...
;             PG8_BAR; PG8_WAIT_L(0); PG8_MMA(0, 1, At, B1); PG8_BAR;
;             PG8_LDA(At, 1, 1); PG8_STAGE(PG8_SA(1, 0), a3, voffA);
;             PG8_BAR; PG8_WAIT_L(0); PG8_MMA(1, 0, At, B0); PG8_BAR; PG8_SCHED;
;             PG8_STAGE(PG8_SB(1, 1), b3 + hstepB, voffB);
;             PG8_WAIT_V(6); PG8_BAR; PG8_MMA(1, 1, At, B1); PG8_BAR;
	s_waitcnt lgkmcnt(0)
	v_mfma_f32_16x16x32_bf16 v[62:65], v[180:183], v[202:205], v[62:65]
	v_mfma_f32_16x16x32_bf16 v[58:61], v[188:191], v[202:205], v[58:61]
	v_mfma_f32_16x16x32_bf16 v[54:57], v[180:183], v[210:213], v[54:57]
	v_mfma_f32_16x16x32_bf16 v[46:49], v[188:191], v[210:213], v[46:49]
	v_mfma_f32_16x16x32_bf16 v[38:41], v[180:183], v[218:221], v[38:41]
	v_mfma_f32_16x16x32_bf16 v[30:33], v[188:191], v[218:221], v[30:33]
	v_mfma_f32_16x16x32_bf16 v[22:25], v[180:183], v[226:229], v[22:25]
	v_mfma_f32_16x16x32_bf16 v[14:17], v[188:191], v[226:229], v[14:17]
	v_mfma_f32_16x16x32_bf16 v[62:65], v[184:187], v[206:209], v[62:65]
	v_mfma_f32_16x16x32_bf16 v[58:61], v[198:201], v[206:209], v[58:61]
	v_mfma_f32_16x16x32_bf16 v[54:57], v[184:187], v[214:217], v[54:57]
	v_mfma_f32_16x16x32_bf16 v[46:49], v[198:201], v[214:217], v[46:49]
	v_mfma_f32_16x16x32_bf16 v[38:41], v[184:187], v[222:225], v[38:41]
	v_mfma_f32_16x16x32_bf16 v[30:33], v[198:201], v[222:225], v[30:33]
	v_mfma_f32_16x16x32_bf16 v[22:25], v[184:187], v[230:233], v[22:25]
	v_mfma_f32_16x16x32_bf16 v[14:17], v[198:201], v[230:233], v[14:17]
	s_barrier
	s_add_u32 s14, s14, 0x200080
	s_addc_u32 s15, s15, 0
	s_add_i32 s16, s16, s23
	v_lshl_add_u64 v[152:153], s[14:15], 0, v[0:1]
	s_mov_b32 m0, s16
	s_nop 0
	global_load_lds_dwordx4 v[152:153], off
	v_lshl_add_u64 v[152:153], s[14:15], 0, v[142:143]
	s_add_i32 m0, s16, 0x2000
	s_nop 0
	global_load_lds_dwordx4 v[152:153], off
	s_waitcnt vmcnt(6)
	s_barrier
	v_mfma_f32_16x16x32_bf16 v[50:53], v[234:237], v[202:205], v[50:53]
	v_mfma_f32_16x16x32_bf16 v[42:45], v[242:245], v[202:205], v[42:45]
	v_mfma_f32_16x16x32_bf16 v[34:37], v[234:237], v[210:213], v[34:37]
	v_mfma_f32_16x16x32_bf16 v[26:29], v[242:245], v[210:213], v[26:29]
	v_mfma_f32_16x16x32_bf16 v[18:21], v[234:237], v[218:221], v[18:21]
	v_mfma_f32_16x16x32_bf16 v[10:13], v[242:245], v[218:221], v[10:13]
	v_mfma_f32_16x16x32_bf16 v[6:9], v[234:237], v[226:229], v[6:9]
	v_mfma_f32_16x16x32_bf16 v[2:5], v[242:245], v[226:229], v[2:5]
	v_mfma_f32_16x16x32_bf16 v[50:53], v[238:241], v[206:209], v[50:53]
	v_mfma_f32_16x16x32_bf16 v[42:45], v[246:249], v[206:209], v[42:45]
	v_mfma_f32_16x16x32_bf16 v[34:37], v[238:241], v[214:217], v[34:37]
	v_mfma_f32_16x16x32_bf16 v[26:29], v[246:249], v[214:217], v[26:29]
	v_mfma_f32_16x16x32_bf16 v[18:21], v[238:241], v[222:225], v[18:21]
	v_mfma_f32_16x16x32_bf16 v[10:13], v[246:249], v[222:225], v[10:13]
	v_mfma_f32_16x16x32_bf16 v[6:9], v[238:241], v[230:233], v[6:9]
	v_mfma_f32_16x16x32_bf16 v[2:5], v[246:249], v[230:233], v[2:5]
	s_add_i32 s38, s38, 2
	s_add_u32 s12, s12, 0x100
	s_addc_u32 s13, s13, 0
	s_add_u32 s36, s36, 0x100
	s_addc_u32 s37, s37, 0
	s_cmpk_gt_u32 s38, 0x7d
	s_barrier
	s_cbranch_scc0 .LBB0_47
; __device__ __forceinline__ unsigned cvt_pk_bf16(float lo, float hi) { unsigned r; asm("v_cvt_pk_bf16_f32 %0, %1, %2" : "=v"(r) : "v"(lo), "v"(hi)); return r; }
; #define PG8_WAIT_V(n) asm volatile("s_waitcnt vmcnt(" #n ")" ::: "memory")
; #define PG8_BAR __builtin_amdgcn_s_barrier()
;     __device__ __forceinline__ void operator()(const f32x4 (&acc)[2][2][4][2], const Unit& u, int wr, int wc, int fr, int fq) const {
;         const int row0 = u.pm * BM + wr * 64 + fr, col0 = u.pn * BM + wc * 32 + 8 * fq;
; #pragma unroll
;         for (int ai = 0; ai < 2; ++ai)
; #pragma unroll
;             for (int m = 0; m < 4; ++m) { bf16_t* rowp = O + (size_t)(row0 + ai * HALF + m * 16) * ldc + col0;
; #pragma unroll
;                 for (int bj = 0; bj < 2; ++bj) { f32x4 v0 = acc[ai][bj][m][0], v1 = acc[ai][bj][m][1];
;                     if (ACT == 1) {
; #pragma unroll
;                         for (int j = 0; j < 4; ++j) { const float a = fmaxf(v0[j], 0.f), b = fmaxf(v1[j], 0.f); v0[j] = a * a; v1[j] = b * b; } }
;                     u32x4 w; w.x = cvt_pk_bf16(v0[0], v0[1]); w.y = cvt_pk_bf16(v0[2], v0[3]); w.z = cvt_pk_bf16(v1[0], v1[1]); w.w = cvt_pk_bf16(v1[2], v1[3]);
;                     *(u32x4*)(rowp + bj * HALF) = w; } }
; template <class Epi, bool SEG>
; __device__ __forceinline__ void gemm_phase(LAS unsigned char* lds, const Gemm g, const StaticOrder& S, const Epi& E) {
;     ...
;         E(acc, cur, wr, wc, fr, fq);
;         if (!has_next) break;
; #pragma unroll
;         for (int a = 0; a < 2; ++a)
; #pragma unroll
;             for (int b = 0; b < 2; ++b)
; #pragma unroll
;                 for (int m = 0; m < 4; ++m)
; #pragma unroll
;                     for (int n = 0; n < 2; ++n) acc[a][b][m][n] = (f32x4){0.f, 0.f, 0.f, 0.f};
;         cur = nxt; cA = nA; cB = nB; ++ui;
;     }
;     PG8_WAIT_V(0);
;     if (wr == 0) PG8_BAR;
;     PG8_BAR;
	v_lshl_add_u32 v158, s8, 8, v154
	v_lshl_or_b32 v152, s31, 8, v156
	v_ashrrev_i32_e32 v159, 31, v158
	v_readlane_b32 s12, v253, 6
	v_ashrrev_i32_e32 v153, 31, v152
	v_lshlrev_b64 v[180:181], 12, v[158:159]
	v_readlane_b32 s13, v253, 7
	v_lshlrev_b64 v[182:183], 1, v[152:153]
	s_mov_b32 s1, 0x80000
	v_lshl_add_u64 v[180:181], s[12:13], 0, v[180:181]
	v_lshl_add_u64 v[152:153], v[180:181], 0, v[182:183]
	v_cvt_pk_bf16_f32 v62, v62, v63
	v_cvt_pk_bf16_f32 v63, v64, v65
	v_cvt_pk_bf16_f32 v64, v58, v59
	v_add_co_u32_e32 v58, vcc, s1, v152
	v_cvt_pk_bf16_f32 v114, v114, v115
	v_cvt_pk_bf16_f32 v115, v116, v117
	v_cvt_pk_bf16_f32 v116, v106, v107
	v_or_b32_e32 v106, 16, v158
	v_cvt_pk_bf16_f32 v98, v98, v99
	v_cvt_pk_bf16_f32 v99, v100, v101
	v_cvt_pk_bf16_f32 v100, v90, v91
	v_or_b32_e32 v90, 32, v158
	v_cvt_pk_bf16_f32 v86, v86, v87
	v_cvt_pk_bf16_f32 v87, v88, v89
	v_cvt_pk_bf16_f32 v88, v78, v79
	v_or_b32_e32 v78, 48, v158
	v_addc_co_u32_e32 v59, vcc, 0, v153, vcc
	s_mov_b32 s1, 0x90000
	v_ashrrev_i32_e32 v107, 31, v106
	v_ashrrev_i32_e32 v91, 31, v90
	v_ashrrev_i32_e32 v79, 31, v78
	v_cvt_pk_bf16_f32 v50, v50, v51
	v_cvt_pk_bf16_f32 v51, v52, v53
	v_cvt_pk_bf16_f32 v53, v44, v45
	v_cvt_pk_bf16_f32 v44, v46, v47
	v_add_co_u32_e32 v46, vcc, s1, v152
	v_lshlrev_b64 v[106:107], 12, v[106:107]
	v_lshlrev_b64 v[90:91], 12, v[90:91]
	v_lshlrev_b64 v[78:79], 12, v[78:79]
	v_addc_co_u32_e32 v47, vcc, 0, v153, vcc
	s_mov_b32 s1, 0xa0000
	v_lshl_add_u64 v[106:107], s[12:13], 0, v[106:107]
	v_lshl_add_u64 v[90:91], s[12:13], 0, v[90:91]
	v_lshl_add_u64 v[78:79], s[12:13], 0, v[78:79]
	s_mov_b64 s[12:13], 0x80000
	v_cvt_pk_bf16_f32 v34, v34, v35
	v_cvt_pk_bf16_f32 v35, v36, v37
	v_cvt_pk_bf16_f32 v37, v28, v29
	v_cvt_pk_bf16_f32 v28, v30, v31
	v_add_co_u32_e32 v30, vcc, s1, v152
	v_cvt_pk_bf16_f32 v70, v70, v71
	v_cvt_pk_bf16_f32 v71, v72, v73
	v_cvt_pk_bf16_f32 v72, v66, v67
	v_lshl_add_u64 v[66:67], v[152:153], 0, s[12:13]
	s_mov_b64 s[12:13], 0x90000
	v_addc_co_u32_e32 v31, vcc, 0, v153, vcc
	s_mov_b32 s1, 0xb0000
	v_cvt_pk_bf16_f32 v117, v108, v109
	global_store_dwordx4 v[152:153], v[114:117], off offset:256
	v_cvt_pk_bf16_f32 v52, v42, v43
	global_store_dwordx4 v[66:67], v[50:53], off offset:256
	v_cvt_pk_bf16_f32 v18, v18, v19
	v_cvt_pk_bf16_f32 v19, v20, v21
	v_cvt_pk_bf16_f32 v21, v12, v13
	s_nop 0
	v_lshl_add_u64 v[114:115], v[106:107], 0, v[182:183]
	v_cvt_pk_bf16_f32 v12, v14, v15
	v_lshl_add_u64 v[50:51], v[152:153], 0, s[12:13]
	s_mov_b64 s[12:13], 0xa0000
	v_add_co_u32_e32 v14, vcc, s1, v152
	v_cvt_pk_bf16_f32 v101, v92, v93
	global_store_dwordx4 v[114:115], v[98:101], off offset:256
	v_cvt_pk_bf16_f32 v36, v26, v27
	global_store_dwordx4 v[50:51], v[34:37], off offset:256
	v_addc_co_u32_e32 v15, vcc, 0, v153, vcc
	v_lshl_add_u64 v[98:99], v[90:91], 0, v[182:183]
	v_lshl_add_u64 v[34:35], v[152:153], 0, s[12:13]
	s_mov_b64 s[12:13], 0xb0000
	v_cvt_pk_bf16_f32 v89, v80, v81
	global_store_dwordx4 v[98:99], v[86:89], off offset:256
	v_cvt_pk_bf16_f32 v20, v10, v11
	global_store_dwordx4 v[34:35], v[18:21], off offset:256
	s_and_b64 vcc, exec, s[2:3]
	v_lshl_add_u64 v[86:87], v[78:79], 0, v[182:183]
	v_lshl_add_u64 v[18:19], v[152:153], 0, s[12:13]
	s_mov_b32 s31, s0
	s_mov_b32 s8, s4
	s_mov_b64 s[14:15], s[10:11]
	s_mov_b64 s[12:13], s[6:7]
	v_cvt_pk_bf16_f32 v126, v126, v127
	v_cvt_pk_bf16_f32 v127, v128, v129
	v_cvt_pk_bf16_f32 v128, v122, v123
	v_cvt_pk_bf16_f32 v129, v124, v125
	global_store_dwordx4 v[152:153], v[126:129], off
	v_cvt_pk_bf16_f32 v106, v118, v119
	v_cvt_pk_bf16_f32 v107, v120, v121
	v_cvt_pk_bf16_f32 v108, v110, v111
	v_cvt_pk_bf16_f32 v109, v112, v113
	global_store_dwordx4 v[114:115], v[106:109], off
	v_cvt_pk_bf16_f32 v90, v102, v103
	v_cvt_pk_bf16_f32 v91, v104, v105
	v_cvt_pk_bf16_f32 v92, v94, v95
	v_cvt_pk_bf16_f32 v93, v96, v97
	global_store_dwordx4 v[98:99], v[90:93], off
	v_cvt_pk_bf16_f32 v78, v82, v83
	v_cvt_pk_bf16_f32 v79, v84, v85
	v_cvt_pk_bf16_f32 v80, v74, v75
	v_cvt_pk_bf16_f32 v81, v76, v77
	global_store_dwordx4 v[86:87], v[78:81], off
	v_cvt_pk_bf16_f32 v73, v68, v69
	global_store_dwordx4 v[86:87], v[70:73], off offset:256
	v_cvt_pk_bf16_f32 v65, v60, v61
	global_store_dwordx4 v[58:59], v[62:65], off
	v_cvt_pk_bf16_f32 v42, v54, v55
	v_cvt_pk_bf16_f32 v43, v56, v57
	v_cvt_pk_bf16_f32 v45, v48, v49
	global_store_dwordx4 v[46:47], v[42:45], off
	v_cvt_pk_bf16_f32 v26, v38, v39
	v_cvt_pk_bf16_f32 v27, v40, v41
	v_cvt_pk_bf16_f32 v29, v32, v33
	global_store_dwordx4 v[30:31], v[26:29], off
	v_cvt_pk_bf16_f32 v10, v22, v23
	v_cvt_pk_bf16_f32 v11, v24, v25
	v_cvt_pk_bf16_f32 v13, v16, v17
	global_store_dwordx4 v[14:15], v[10:13], off
	v_cvt_pk_bf16_f32 v6, v6, v7
	v_cvt_pk_bf16_f32 v7, v8, v9
	v_cvt_pk_bf16_f32 v8, v2, v3
	v_cvt_pk_bf16_f32 v9, v4, v5
	global_store_dwordx4 v[18:19], v[6:9], off offset:256
	s_cbranch_vccz .LBB0_44
	s_waitcnt vmcnt(0)
	s_cmpk_gt_u32 s21, 0xff
	v_readlane_b32 s29, v254, 8
	s_cbranch_scc1 .LBB0_51
	s_barrier

; #define PG8_STAGE(bufoff, gbase, voff) do { _Pragma("unroll") for (int _i = 0; _i < 2; ++_i) \
;         __builtin_amdgcn_global_load_lds((const unsigned*)((const char*)(gbase) + (voff)[_i]), (LAS unsigned*)(lds + (bufoff) + ldsw + _i * 8192), 16, 0, 0); } while (0)
; #define PG8_LDA(dst, b, h) do { _Pragma("unroll") for (int m = 0; m < 4; ++m) _Pragma("unroll") for (int k = 0; k < 2; ++k) dst[m][k] = *(const LAS bf16x8*)(lds + PG8_SA(b, h) + aoff + m * 2048 + k * 1024); } while (0)
; #define PG8_LDB(dst, b, h) do { _Pragma("unroll") for (int n = 0; n < 2; ++n) _Pragma("unroll") for (int k = 0; k < 2; ++k) dst[n][k] = *(const LAS bf16x8*)(lds + PG8_SB(b, h) + boff + n * 2048 + k * 1024); } while (0)
; #define PG8_MMA(ai, bj, At, Bt) do { __builtin_amdgcn_s_setprio(1); _Pragma("unroll") for (int m = 0; m < 4; ++m) _Pragma("unroll") for (int n = 0; n < 2; ++n) _Pragma("unroll") for (int k = 0; k < 2; ++k) \
;         acc[ai][bj][m][n] = __builtin_amdgcn_mfma_f32_16x16x32_bf16(Bt[n][k], At[m][k], acc[ai][bj][m][n], 0, 0, 0); __builtin_amdgcn_s_setprio(0); } while (0)
; #define PG8_WAIT_L(n) asm volatile("s_waitcnt lgkmcnt(" #n ")" ::: "memory")
; #define PG8_BAR __builtin_amdgcn_s_barrier()
; #define PG8_SCHED __builtin_amdgcn_sched_barrier(0)
; template <class Epi, bool SEG>
; __device__ __forceinline__ void gemm_phase(LAS unsigned char* lds, const Gemm g, const StaticOrder& S, const Epi& E) {
;     ...
;         for (int t = 0; t < nt; t += 2) {
;             const bool last = (t == nt - 2);
;             const char* a1 = cA + akoff<SEG>(t) + kstep;
;             const char* a2 = last ? nA : cA + akoff<SEG>(t + 2); const char* b2 = last ? nB : cB + (size_t)(t + 2) * kstep;
;             const char* a3 = a2 + kstep; const char* b3 = b2 + kstep;
;             PG8_LDB(B0, 0, 0); PG8_SCHED; PG8_LDA(At, 0, 0); PG8_STAGE(PG8_SA(1, 1), a1 + hstepA, voffA);
;             PG8_WAIT_L(8); PG8_BAR; PG8_WAIT_L(0); PG8_MMA(0, 0, At, B0); PG8_BAR; PG8_SCHED;
;             PG8_LDB(B1, 0, 1); PG8_STAGE(PG8_SB(0, 0), b2, voffB);
;             PG8_BAR; PG8_WAIT_L(0); PG8_MMA(0, 1, At, B1); PG8_BAR;
;             PG8_LDA(At, 0, 1); PG8_STAGE(PG8_SA(0, 0), a2, voffA);
;             PG8_BAR; PG8_WAIT_L(0); PG8_MMA(1, 0, At, B0); PG8_BAR; PG8_SCHED;
.LBB0_69:
	s_add_u32 s14, s12, 0xfff80080
	s_addc_u32 s15, s13, -1
	s_add_i32 s39, 0, 0x10000
	v_add_u32_e32 v152, s39, v155
	ds_read_b128 v[180:183], v152
	ds_read_b128 v[184:187], v152 offset:1024
	ds_read_b128 v[188:191], v152 offset:2048
	ds_read_b128 v[198:201], v152 offset:3072
	s_cmp_eq_u32 s38, 28
	s_cselect_b32 s17, s5, s15
	s_cselect_b32 s16, s34, s14
	s_cselect_b32 s15, s1, s37
	s_cselect_b32 s14, s35, s36
	v_lshl_add_u64 v[152:153], s[12:13], 0, v[148:149]
	s_add_i32 m0, s11, 0xc000
	ds_read_b128 v[202:205], v157
	ds_read_b128 v[206:209], v157 offset:1024
	ds_read_b128 v[210:213], v157 offset:2048
	ds_read_b128 v[214:217], v157 offset:3072
	ds_read_b128 v[218:221], v157 offset:4096
	ds_read_b128 v[222:225], v157 offset:5120
	ds_read_b128 v[226:229], v157 offset:6144
	ds_read_b128 v[230:233], v157 offset:7168
	global_load_lds_dwordx4 v[152:153], off
	v_lshl_add_u64 v[152:153], s[12:13], 0, v[150:151]
	s_add_i32 m0, s11, 0xe000
	s_nop 0
	global_load_lds_dwordx4 v[152:153], off
	s_waitcnt lgkmcnt(8)
	s_barrier
	s_waitcnt lgkmcnt(0)
	v_mfma_f32_16x16x32_bf16 v[126:129], v[180:183], v[202:205], v[126:129]
	v_mfma_f32_16x16x32_bf16 v[122:125], v[188:191], v[202:205], v[122:125]
	v_mfma_f32_16x16x32_bf16 v[110:113], v[180:183], v[210:213], v[110:113]
	v_mfma_f32_16x16x32_bf16 v[106:109], v[188:191], v[210:213], v[106:109]
	v_mfma_f32_16x16x32_bf16 v[94:97], v[180:183], v[218:221], v[94:97]
	v_mfma_f32_16x16x32_bf16 v[90:93], v[188:191], v[218:221], v[90:93]
	v_mfma_f32_16x16x32_bf16 v[78:81], v[180:183], v[226:229], v[78:81]
	v_mfma_f32_16x16x32_bf16 v[74:77], v[188:191], v[226:229], v[74:77]
	v_mfma_f32_16x16x32_bf16 v[126:129], v[184:187], v[206:209], v[126:129]
	v_mfma_f32_16x16x32_bf16 v[122:125], v[198:201], v[206:209], v[122:125]
	v_mfma_f32_16x16x32_bf16 v[110:113], v[184:187], v[214:217], v[110:113]
	v_mfma_f32_16x16x32_bf16 v[106:109], v[198:201], v[214:217], v[106:109]
	v_mfma_f32_16x16x32_bf16 v[94:97], v[184:187], v[222:225], v[94:97]
	v_mfma_f32_16x16x32_bf16 v[90:93], v[198:201], v[222:225], v[90:93]
	v_mfma_f32_16x16x32_bf16 v[78:81], v[184:187], v[230:233], v[78:81]
	v_mfma_f32_16x16x32_bf16 v[74:77], v[198:201], v[230:233], v[74:77]
	s_barrier
	s_add_i32 s42, 0, 0x14000
	v_add_u32_e32 v152, s42, v155
	s_add_i32 s39, s39, s24
	ds_read_b128 v[234:237], v152
	ds_read_b128 v[238:241], v152 offset:1024
	ds_read_b128 v[242:245], v152 offset:2048
	ds_read_b128 v[246:249], v152 offset:3072
	v_lshl_add_u64 v[152:153], s[14:15], 0, v[0:1]
	s_mov_b32 m0, s39
	v_lshl_add_u64 v[158:159], s[14:15], 0, v[146:147]
	global_load_lds_dwordx4 v[152:153], off
	s_add_i32 m0, s39, 0x2000
	s_nop 0
	global_load_lds_dwordx4 v[158:159], off
	s_barrier
	s_waitcnt lgkmcnt(0)
	v_mfma_f32_16x16x32_bf16 v[118:121], v[234:237], v[202:205], v[118:121]
	v_mfma_f32_16x16x32_bf16 v[114:117], v[242:245], v[202:205], v[114:117]
	v_mfma_f32_16x16x32_bf16 v[102:105], v[234:237], v[210:213], v[102:105]
	v_mfma_f32_16x16x32_bf16 v[98:101], v[242:245], v[210:213], v[98:101]
	v_mfma_f32_16x16x32_bf16 v[86:89], v[234:237], v[218:221], v[86:89]
	v_mfma_f32_16x16x32_bf16 v[82:85], v[242:245], v[218:221], v[82:85]
	v_mfma_f32_16x16x32_bf16 v[70:73], v[234:237], v[226:229], v[70:73]
	v_mfma_f32_16x16x32_bf16 v[66:69], v[242:245], v[226:229], v[66:69]
	v_mfma_f32_16x16x32_bf16 v[118:121], v[238:241], v[206:209], v[118:121]
	v_mfma_f32_16x16x32_bf16 v[114:117], v[246:249], v[206:209], v[114:117]
	v_mfma_f32_16x16x32_bf16 v[102:105], v[238:241], v[214:217], v[102:105]
	v_mfma_f32_16x16x32_bf16 v[98:101], v[246:249], v[214:217], v[98:101]
	v_mfma_f32_16x16x32_bf16 v[86:89], v[238:241], v[222:225], v[86:89]
	v_mfma_f32_16x16x32_bf16 v[82:85], v[246:249], v[222:225], v[82:85]
	v_mfma_f32_16x16x32_bf16 v[70:73], v[238:241], v[230:233], v[70:73]
	v_mfma_f32_16x16x32_bf16 v[66:69], v[246:249], v[230:233], v[66:69]
	s_mov_b32 m0, s11
	v_lshl_add_u64 v[192:193], s[16:17], 0, v[142:143]
	s_barrier
	ds_read_b128 v[202:205], v157 offset:16384
	ds_read_b128 v[206:209], v157 offset:17408
	ds_read_b128 v[210:213], v157 offset:18432
	ds_read_b128 v[214:217], v157 offset:19456
	ds_read_b128 v[218:221], v157 offset:20480
	ds_read_b128 v[222:225], v157 offset:21504
	ds_read_b128 v[226:229], v157 offset:22528
	ds_read_b128 v[230:233], v157 offset:23552
	global_load_lds_dwordx4 v[192:193], off
	v_lshl_add_u64 v[250:251], s[16:17], 0, v[144:145]
	s_mov_b32 m0, s25
	s_nop 0
	global_load_lds_dwordx4 v[250:251], off
	s_barrier
	s_waitcnt lgkmcnt(0)
	v_mfma_f32_16x16x32_bf16 v[62:65], v[180:183], v[202:205], v[62:65]
	v_mfma_f32_16x16x32_bf16 v[58:61], v[188:191], v[202:205], v[58:61]
	v_mfma_f32_16x16x32_bf16 v[46:49], v[180:183], v[210:213], v[46:49]
	v_mfma_f32_16x16x32_bf16 v[42:45], v[188:191], v[210:213], v[42:45]
	v_mfma_f32_16x16x32_bf16 v[30:33], v[180:183], v[218:221], v[30:33]
	v_mfma_f32_16x16x32_bf16 v[26:29], v[188:191], v[218:221], v[26:29]
	v_mfma_f32_16x16x32_bf16 v[14:17], v[180:183], v[226:229], v[14:17]
	v_mfma_f32_16x16x32_bf16 v[10:13], v[188:191], v[226:229], v[10:13]
	v_mfma_f32_16x16x32_bf16 v[62:65], v[184:187], v[206:209], v[62:65]
	v_mfma_f32_16x16x32_bf16 v[58:61], v[198:201], v[206:209], v[58:61]
	v_mfma_f32_16x16x32_bf16 v[46:49], v[184:187], v[214:217], v[46:49]
	v_mfma_f32_16x16x32_bf16 v[42:45], v[198:201], v[214:217], v[42:45]
	v_mfma_f32_16x16x32_bf16 v[30:33], v[184:187], v[222:225], v[30:33]
	v_mfma_f32_16x16x32_bf16 v[26:29], v[198:201], v[222:225], v[26:29]
	v_mfma_f32_16x16x32_bf16 v[14:17], v[184:187], v[230:233], v[14:17]
	v_mfma_f32_16x16x32_bf16 v[10:13], v[198:201], v[230:233], v[10:13]
	s_barrier
; #define PG8_STAGE(bufoff, gbase, voff) do { _Pragma("unroll") for (int _i = 0; _i < 2; ++_i) \
;         __builtin_amdgcn_global_load_lds((const unsigned*)((const char*)(gbase) + (voff)[_i]), (LAS unsigned*)(lds + (bufoff) + ldsw + _i * 8192), 16, 0, 0); } while (0)
; #define PG8_LDA(dst, b, h) do { _Pragma("unroll") for (int m = 0; m < 4; ++m) _Pragma("unroll") for (int k = 0; k < 2; ++k) dst[m][k] = *(const LAS bf16x8*)(lds + PG8_SA(b, h) + aoff + m * 2048 + k * 1024); } while (0)
; #define PG8_LDB(dst, b, h) do { _Pragma("unroll") for (int n = 0; n < 2; ++n) _Pragma("unroll") for (int k = 0; k < 2; ++k) dst[n][k] = *(const LAS bf16x8*)(lds + PG8_SB(b, h) + boff + n * 2048 + k * 1024); } while (0)
; #define PG8_MMA(ai, bj, At, Bt) do { __builtin_amdgcn_s_setprio(1); _Pragma("unroll") for (int m = 0; m < 4; ++m) _Pragma("unroll") for (int n = 0; n < 2; ++n) _Pragma("unroll") for (int k = 0; k < 2; ++k) \
;         acc[ai][bj][m][n] = __builtin_amdgcn_mfma_f32_16x16x32_bf16(Bt[n][k], At[m][k], acc[ai][bj][m][n], 0, 0, 0); __builtin_amdgcn_s_setprio(0); } while (0)
; #define PG8_WAIT_V(n) asm volatile("s_waitcnt vmcnt(" #n ")" ::: "memory")
; #define PG8_WAIT_L(n) asm volatile("s_waitcnt lgkmcnt(" #n ")" ::: "memory")
; #define PG8_BAR __builtin_amdgcn_s_barrier()
; #define PG8_SCHED __builtin_amdgcn_sched_barrier(0)
; template <class Epi, bool SEG>
; __device__ __forceinline__ void gemm_phase(LAS unsigned char* lds, const Gemm g, const StaticOrder& S, const Epi& E) {
;     ...
;             PG8_STAGE(PG8_SB(0, 1), b2 + hstepB, voffB);
;             PG8_WAIT_V(6); PG8_BAR; PG8_MMA(1, 1, At, B1); PG8_BAR;
;             PG8_LDB(B0, 1, 0); PG8_SCHED; PG8_LDA(At, 1, 0); PG8_STAGE(PG8_SA(0, 1), a2 + hstepA, voffA);
;             PG8_WAIT_L(8); PG8_BAR; PG8_WAIT_L(0); PG8_MMA(0, 0, At, B0); PG8_BAR; PG8_SCHED;
;             PG8_LDB(B1, 1, 1); PG8_STAGE(PG8_SB(1, 0), b3, voffB);
;             PG8_BAR; PG8_WAIT_L(0); PG8_MMA(0, 1, At, B1); PG8_BAR;
;             PG8_LDA(At, 1, 1); PG8_STAGE(PG8_SA(1, 0), a3, voffA);
;             PG8_BAR; PG8_WAIT_L(0); PG8_MMA(1, 0, At, B0); PG8_BAR; PG8_SCHED;
	s_add_u32 s40, s14, 0x80000
	s_addc_u32 s41, s15, 0
	s_add_i32 s39, s42, s24
	v_lshl_add_u64 v[180:181], s[40:41], 0, v[0:1]
	s_mov_b32 m0, s39
	s_nop 0
	global_load_lds_dwordx4 v[180:181], off
	v_lshl_add_u64 v[180:181], s[40:41], 0, v[146:147]
	s_add_i32 m0, s39, 0x2000
	s_nop 0
	global_load_lds_dwordx4 v[180:181], off
	s_waitcnt vmcnt(6)
	s_barrier
	v_mfma_f32_16x16x32_bf16 v[54:57], v[234:237], v[202:205], v[54:57]
	v_mfma_f32_16x16x32_bf16 v[50:53], v[242:245], v[202:205], v[50:53]
	v_mfma_f32_16x16x32_bf16 v[38:41], v[234:237], v[210:213], v[38:41]
	v_mfma_f32_16x16x32_bf16 v[34:37], v[242:245], v[210:213], v[34:37]
	v_mfma_f32_16x16x32_bf16 v[22:25], v[234:237], v[218:221], v[22:25]
	v_mfma_f32_16x16x32_bf16 v[18:21], v[242:245], v[218:221], v[18:21]
	v_mfma_f32_16x16x32_bf16 v[6:9], v[234:237], v[226:229], v[6:9]
	v_mfma_f32_16x16x32_bf16 v[2:5], v[242:245], v[226:229], v[2:5]
	v_mfma_f32_16x16x32_bf16 v[54:57], v[238:241], v[206:209], v[54:57]
	v_mfma_f32_16x16x32_bf16 v[50:53], v[246:249], v[206:209], v[50:53]
	v_mfma_f32_16x16x32_bf16 v[38:41], v[238:241], v[214:217], v[38:41]
	v_mfma_f32_16x16x32_bf16 v[34:37], v[246:249], v[214:217], v[34:37]
	v_mfma_f32_16x16x32_bf16 v[22:25], v[238:241], v[222:225], v[22:25]
	v_mfma_f32_16x16x32_bf16 v[18:21], v[246:249], v[222:225], v[18:21]
	v_mfma_f32_16x16x32_bf16 v[6:9], v[238:241], v[230:233], v[6:9]
	v_mfma_f32_16x16x32_bf16 v[2:5], v[246:249], v[230:233], v[2:5]
	s_add_i32 s39, 0, 0x18000
	v_add_u32_e32 v179, s39, v155
	s_barrier
	ds_read_b128 v[180:183], v179
	ds_read_b128 v[184:187], v179 offset:1024
	ds_read_b128 v[188:191], v179 offset:2048
	ds_read_b128 v[198:201], v179 offset:3072
	s_add_u32 s16, s16, 0x80000
	s_addc_u32 s17, s17, 0
	s_mov_b32 m0, s26
	v_lshl_add_u64 v[234:235], s[16:17], 0, v[142:143]
	ds_read_b128 v[202:205], v157 offset:32768
	ds_read_b128 v[206:209], v157 offset:33792
	ds_read_b128 v[210:213], v157 offset:34816
	ds_read_b128 v[214:217], v157 offset:35840
	ds_read_b128 v[218:221], v157 offset:36864
	ds_read_b128 v[222:225], v157 offset:37888
	ds_read_b128 v[226:229], v157 offset:38912
	ds_read_b128 v[230:233], v157 offset:39936
	global_load_lds_dwordx4 v[234:235], off
	v_lshl_add_u64 v[234:235], s[16:17], 0, v[144:145]
	s_mov_b32 m0, s27
	s_nop 0
	global_load_lds_dwordx4 v[234:235], off
	s_waitcnt lgkmcnt(8)
	s_barrier
	s_waitcnt lgkmcnt(0)
	v_mfma_f32_16x16x32_bf16 v[126:129], v[180:183], v[202:205], v[126:129]
	v_mfma_f32_16x16x32_bf16 v[122:125], v[188:191], v[202:205], v[122:125]
	v_mfma_f32_16x16x32_bf16 v[110:113], v[180:183], v[210:213], v[110:113]
	v_mfma_f32_16x16x32_bf16 v[106:109], v[188:191], v[210:213], v[106:109]
	v_mfma_f32_16x16x32_bf16 v[94:97], v[180:183], v[218:221], v[94:97]
	v_mfma_f32_16x16x32_bf16 v[90:93], v[188:191], v[218:221], v[90:93]
	v_mfma_f32_16x16x32_bf16 v[78:81], v[180:183], v[226:229], v[78:81]
	v_mfma_f32_16x16x32_bf16 v[74:77], v[188:191], v[226:229], v[74:77]
	v_mfma_f32_16x16x32_bf16 v[126:129], v[184:187], v[206:209], v[126:129]
	v_mfma_f32_16x16x32_bf16 v[122:125], v[198:201], v[206:209], v[122:125]
	v_mfma_f32_16x16x32_bf16 v[110:113], v[184:187], v[214:217], v[110:113]
	v_mfma_f32_16x16x32_bf16 v[106:109], v[198:201], v[214:217], v[106:109]
	v_mfma_f32_16x16x32_bf16 v[94:97], v[184:187], v[222:225], v[94:97]
	v_mfma_f32_16x16x32_bf16 v[90:93], v[198:201], v[222:225], v[90:93]
	v_mfma_f32_16x16x32_bf16 v[78:81], v[184:187], v[230:233], v[78:81]
	v_mfma_f32_16x16x32_bf16 v[74:77], v[198:201], v[230:233], v[74:77]
	s_barrier
	s_add_i32 s16, 0, 0x1c000
	s_add_i32 s17, s39, s24
	v_add_u32_e32 v179, s16, v155
	v_lshl_add_u64 v[152:153], v[152:153], 0, s[96:97]
	s_mov_b32 m0, s17
	ds_read_b128 v[234:237], v179
	ds_read_b128 v[238:241], v179 offset:1024
	ds_read_b128 v[242:245], v179 offset:2048
	ds_read_b128 v[246:249], v179 offset:3072
	global_load_lds_dwordx4 v[152:153], off
	v_lshl_add_u64 v[152:153], v[158:159], 0, s[96:97]
	s_add_i32 m0, s17, 0x2000
	s_nop 0
	global_load_lds_dwordx4 v[152:153], off
	s_barrier
	s_waitcnt lgkmcnt(0)
	v_mfma_f32_16x16x32_bf16 v[118:121], v[234:237], v[202:205], v[118:121]
	v_mfma_f32_16x16x32_bf16 v[114:117], v[242:245], v[202:205], v[114:117]
	v_mfma_f32_16x16x32_bf16 v[102:105], v[234:237], v[210:213], v[102:105]
	v_mfma_f32_16x16x32_bf16 v[98:101], v[242:245], v[210:213], v[98:101]
	v_mfma_f32_16x16x32_bf16 v[86:89], v[234:237], v[218:221], v[86:89]
	v_mfma_f32_16x16x32_bf16 v[82:85], v[242:245], v[218:221], v[82:85]
	v_mfma_f32_16x16x32_bf16 v[70:73], v[234:237], v[226:229], v[70:73]
	v_mfma_f32_16x16x32_bf16 v[66:69], v[242:245], v[226:229], v[66:69]
	v_mfma_f32_16x16x32_bf16 v[118:121], v[238:241], v[206:209], v[118:121]
	v_mfma_f32_16x16x32_bf16 v[114:117], v[246:249], v[206:209], v[114:117]
	v_mfma_f32_16x16x32_bf16 v[102:105], v[238:241], v[214:217], v[102:105]
	v_mfma_f32_16x16x32_bf16 v[98:101], v[246:249], v[214:217], v[98:101]
	v_mfma_f32_16x16x32_bf16 v[86:89], v[238:241], v[222:225], v[86:89]
	v_mfma_f32_16x16x32_bf16 v[82:85], v[246:249], v[222:225], v[82:85]
	v_mfma_f32_16x16x32_bf16 v[70:73], v[238:241], v[230:233], v[70:73]
	v_mfma_f32_16x16x32_bf16 v[66:69], v[246:249], v[230:233], v[66:69]
	s_mov_b32 m0, s28
	v_lshl_add_u64 v[152:153], v[192:193], 0, s[96:97]
	s_barrier
	ds_read_b128 v[202:205], v157 offset:49152
	ds_read_b128 v[206:209], v157 offset:50176
	ds_read_b128 v[210:213], v157 offset:51200
	ds_read_b128 v[214:217], v157 offset:52224
	ds_read_b128 v[218:221], v157 offset:53248
	ds_read_b128 v[222:225], v157 offset:54272
	ds_read_b128 v[226:229], v157 offset:55296
	ds_read_b128 v[230:233], v157 offset:56320
	global_load_lds_dwordx4 v[152:153], off
	v_lshl_add_u64 v[152:153], v[250:251], 0, s[96:97]
	s_mov_b32 m0, s29
	s_nop 0
	global_load_lds_dwordx4 v[152:153], off
	s_barrier
; __device__ __forceinline__ unsigned cvt_pk_bf16(float lo, float hi) { unsigned r; asm("v_cvt_pk_bf16_f32 %0, %1, %2" : "=v"(r) : "v"(lo), "v"(hi)); return r; }
; #define PG8_STAGE(bufoff, gbase, voff) do { _Pragma("unroll") for (int _i = 0; _i < 2; ++_i) \
;         __builtin_amdgcn_global_load_lds((const unsigned*)((const char*)(gbase) + (voff)[_i]), (LAS unsigned*)(lds + (bufoff) + ldsw + _i * 8192), 16, 0, 0); } while (0)
; #define PG8_LDA(dst, b, h) do { _Pragma("unroll") for (int m = 0; m < 4; ++m) _Pragma("unroll") for (int k = 0; k < 2; ++k) dst[m][k] = *(const LAS bf16x8*)(lds + PG8_SA(b, h) + aoff + m * 2048 + k * 1024); } while (0)
; #define PG8_WAIT_V(n) asm volatile("s_waitcnt vmcnt(" #n ")" ::: "memory")
; #define PG8_WAIT_L(n) asm volatile("s_waitcnt lgkmcnt(" #n ")" ::: "memory")
; #define PG8_BAR __builtin_amdgcn_s_barrier()
;     __device__ __forceinline__ void operator()(const f32x4 (&acc)[2][2][4][2], const Unit& u, int wr, int wc, int fr, int fq) const {
;         const int row0 = u.pm * BM + wr * 64 + fr, col0 = u.pn * BM + wc * 32 + 8 * fq;
; #pragma unroll
;         for (int ai = 0; ai < 2; ++ai)
; #pragma unroll
;             for (int m = 0; m < 4; ++m) { bf16_t* rowp = O + (size_t)(row0 + ai * HALF + m * 16) * ldc + col0;
; #pragma unroll
;                 for (int bj = 0; bj < 2; ++bj) { f32x4 v0 = acc[ai][bj][m][0], v1 = acc[ai][bj][m][1];
;                     if (ACT == 1) {
; #pragma unroll
;                         for (int j = 0; j < 4; ++j) { const float a = fmaxf(v0[j], 0.f), b = fmaxf(v1[j], 0.f); v0[j] = a * a; v1[j] = b * b; } }
;                     u32x4 w; w.x = cvt_pk_bf16(v0[0], v0[1]); w.y = cvt_pk_bf16(v0[2], v0[3]); w.z = cvt_pk_bf16(v1[0], v1[1]); w.w = cvt_pk_bf16(v1[2], v1[3]);
;                     *(u32x4*)(rowp + bj * HALF) = w; } }
; template <class Epi, bool SEG>
; __device__ __forceinline__ void gemm_phase(LAS unsigned char* lds, const Gemm g, const StaticOrder& S, const Epi& E) {
;     ...
;             PG8_BAR; PG8_WAIT_L(0); PG8_MMA(0, 1, At, B1); PG8_BAR;
;             PG8_LDA(At, 1, 1); PG8_STAGE(PG8_SA(1, 0), a3, voffA);
;             PG8_BAR; PG8_WAIT_L(0); PG8_MMA(1, 0, At, B0); PG8_BAR; PG8_SCHED;
;             PG8_STAGE(PG8_SB(1, 1), b3 + hstepB, voffB);
;             PG8_WAIT_V(6); PG8_BAR; PG8_MMA(1, 1, At, B1); PG8_BAR;
;         }
;         E(acc, cur, wr, wc, fr, fq);
	s_waitcnt lgkmcnt(0)
	v_mfma_f32_16x16x32_bf16 v[62:65], v[180:183], v[202:205], v[62:65]
	v_mfma_f32_16x16x32_bf16 v[58:61], v[188:191], v[202:205], v[58:61]
	v_mfma_f32_16x16x32_bf16 v[46:49], v[180:183], v[210:213], v[46:49]
	v_mfma_f32_16x16x32_bf16 v[42:45], v[188:191], v[210:213], v[42:45]
	v_mfma_f32_16x16x32_bf16 v[30:33], v[180:183], v[218:221], v[30:33]
	v_mfma_f32_16x16x32_bf16 v[26:29], v[188:191], v[218:221], v[26:29]
	v_mfma_f32_16x16x32_bf16 v[14:17], v[180:183], v[226:229], v[14:17]
	v_mfma_f32_16x16x32_bf16 v[10:13], v[188:191], v[226:229], v[10:13]
	v_mfma_f32_16x16x32_bf16 v[62:65], v[184:187], v[206:209], v[62:65]
	v_mfma_f32_16x16x32_bf16 v[58:61], v[198:201], v[206:209], v[58:61]
	v_mfma_f32_16x16x32_bf16 v[46:49], v[184:187], v[214:217], v[46:49]
	v_mfma_f32_16x16x32_bf16 v[42:45], v[198:201], v[214:217], v[42:45]
	v_mfma_f32_16x16x32_bf16 v[30:33], v[184:187], v[222:225], v[30:33]
	v_mfma_f32_16x16x32_bf16 v[26:29], v[198:201], v[222:225], v[26:29]
	v_mfma_f32_16x16x32_bf16 v[14:17], v[184:187], v[230:233], v[14:17]
	v_mfma_f32_16x16x32_bf16 v[10:13], v[198:201], v[230:233], v[10:13]
	s_barrier
	s_add_u32 s14, s14, 0x80080
	s_addc_u32 s15, s15, 0
	s_add_i32 s16, s16, s24
	v_lshl_add_u64 v[152:153], s[14:15], 0, v[0:1]
	s_mov_b32 m0, s16
	s_nop 0
	global_load_lds_dwordx4 v[152:153], off
	v_lshl_add_u64 v[152:153], s[14:15], 0, v[146:147]
	s_add_i32 m0, s16, 0x2000
	s_nop 0
	global_load_lds_dwordx4 v[152:153], off
	s_waitcnt vmcnt(6)
	s_barrier
	v_mfma_f32_16x16x32_bf16 v[54:57], v[234:237], v[202:205], v[54:57]
	v_mfma_f32_16x16x32_bf16 v[50:53], v[242:245], v[202:205], v[50:53]
	v_mfma_f32_16x16x32_bf16 v[38:41], v[234:237], v[210:213], v[38:41]
	v_mfma_f32_16x16x32_bf16 v[34:37], v[242:245], v[210:213], v[34:37]
	v_mfma_f32_16x16x32_bf16 v[22:25], v[234:237], v[218:221], v[22:25]
	v_mfma_f32_16x16x32_bf16 v[18:21], v[242:245], v[218:221], v[18:21]
	v_mfma_f32_16x16x32_bf16 v[6:9], v[234:237], v[226:229], v[6:9]
	v_mfma_f32_16x16x32_bf16 v[2:5], v[242:245], v[226:229], v[2:5]
	v_mfma_f32_16x16x32_bf16 v[54:57], v[238:241], v[206:209], v[54:57]
	v_mfma_f32_16x16x32_bf16 v[50:53], v[246:249], v[206:209], v[50:53]
	v_mfma_f32_16x16x32_bf16 v[38:41], v[238:241], v[214:217], v[38:41]
	v_mfma_f32_16x16x32_bf16 v[34:37], v[246:249], v[214:217], v[34:37]
	v_mfma_f32_16x16x32_bf16 v[22:25], v[238:241], v[222:225], v[22:25]
	v_mfma_f32_16x16x32_bf16 v[18:21], v[246:249], v[222:225], v[18:21]
	v_mfma_f32_16x16x32_bf16 v[6:9], v[238:241], v[230:233], v[6:9]
	v_mfma_f32_16x16x32_bf16 v[2:5], v[246:249], v[230:233], v[2:5]
	s_add_i32 s38, s38, 2
	s_add_u32 s12, s12, 0x100
	s_addc_u32 s13, s13, 0
	s_add_u32 s36, s36, 0x100
	s_addc_u32 s37, s37, 0
	s_cmp_gt_u32 s38, 29
	s_barrier
	s_cbranch_scc0 .LBB0_69
	v_lshl_add_u32 v158, s10, 8, v154
	v_max_f32_e32 v122, v122, v122
	v_ashrrev_i32_e32 v159, 31, v158
	v_max_f32_e32 v122, 0, v122
	v_max_f32_e32 v123, v123, v123
	v_max_f32_e32 v124, v124, v124
	v_lshl_or_b32 v152, s31, 8, v156
	v_lshlrev_b64 v[180:181], 14, v[158:159]
	v_mul_f32_e32 v159, v122, v122
	v_max_f32_e32 v122, v127, v127
	v_max_f32_e32 v123, 0, v123
	v_max_f32_e32 v124, 0, v124
	v_ashrrev_i32_e32 v153, 31, v152
	v_max_f32_e32 v126, v126, v126
	v_max_f32_e32 v122, 0, v122
	v_mul_f32_e32 v127, v123, v123
	v_max_f32_e32 v123, v128, v128
	v_mul_f32_e32 v128, v124, v124
	v_max_f32_e32 v124, v129, v129
	v_max_f32_e32 v125, v125, v125
	v_lshl_add_u64 v[180:181], s[78:79], 0, v[180:181]
	v_lshlrev_b64 v[182:183], 1, v[152:153]
	v_max_f32_e32 v126, 0, v126
	v_mul_f32_e32 v122, v122, v122
	v_max_f32_e32 v123, 0, v123
	v_max_f32_e32 v124, 0, v124
	v_max_f32_e32 v125, 0, v125
	v_max_f32_e32 v114, v114, v114
	v_lshl_add_u64 v[152:153], v[180:181], 0, v[182:183]
	v_mul_f32_e32 v126, v126, v126
	v_mul_f32_e32 v123, v123, v123
	v_mul_f32_e32 v124, v124, v124
	v_mul_f32_e32 v125, v125, v125
	v_cvt_pk_bf16_f32 v122, v126, v122
	v_max_f32_e32 v114, 0, v114
	v_max_f32_e32 v115, v115, v115
	v_max_f32_e32 v116, v116, v116
	v_cvt_pk_bf16_f32 v123, v123, v124
	v_cvt_pk_bf16_f32 v124, v159, v127
	v_cvt_pk_bf16_f32 v125, v128, v125
	global_store_dwordx4 v[152:153], v[122:125], off
	v_max_f32_e32 v115, 0, v115
	v_max_f32_e32 v116, 0, v116
	v_mul_f32_e32 v122, v114, v114
	v_max_f32_e32 v114, v119, v119
	v_max_f32_e32 v118, v118, v118
	v_max_f32_e32 v114, 0, v114
	v_mul_f32_e32 v119, v115, v115
	v_max_f32_e32 v115, v120, v120
	v_mul_f32_e32 v120, v116, v116
	v_max_f32_e32 v116, v121, v121
	v_max_f32_e32 v117, v117, v117
	v_max_f32_e32 v118, 0, v118
	v_mul_f32_e32 v114, v114, v114
	v_max_f32_e32 v115, 0, v115
	v_max_f32_e32 v116, 0, v116
	v_max_f32_e32 v117, 0, v117
	v_mul_f32_e32 v118, v118, v118
	v_mul_f32_e32 v115, v115, v115
	v_mul_f32_e32 v116, v116, v116
	v_mul_f32_e32 v117, v117, v117
	v_cvt_pk_bf16_f32 v114, v118, v114
	v_max_f32_e32 v106, v106, v106
	v_cvt_pk_bf16_f32 v115, v115, v116
	v_cvt_pk_bf16_f32 v116, v122, v119
	v_cvt_pk_bf16_f32 v117, v120, v117
	global_store_dwordx4 v[152:153], v[114:117], off offset:256
	v_max_f32_e32 v106, 0, v106
	v_max_f32_e32 v107, v107, v107
	v_or_b32_e32 v114, 16, v158
	v_max_f32_e32 v108, v108, v108
	v_ashrrev_i32_e32 v115, 31, v114
	v_mul_f32_e32 v116, v106, v106
	v_max_f32_e32 v106, v111, v111
	v_max_f32_e32 v107, 0, v107
	v_max_f32_e32 v108, 0, v108
	v_lshlrev_b64 v[114:115], 14, v[114:115]
	v_max_f32_e32 v110, v110, v110
	v_max_f32_e32 v106, 0, v106
	v_mul_f32_e32 v111, v107, v107
	v_max_f32_e32 v107, v112, v112
	v_mul_f32_e32 v112, v108, v108
	v_max_f32_e32 v108, v113, v113
	v_max_f32_e32 v109, v109, v109
	v_lshl_add_u64 v[114:115], s[78:79], 0, v[114:115]
	v_max_f32_e32 v110, 0, v110
; __device__ __forceinline__ unsigned cvt_pk_bf16(float lo, float hi) { unsigned r; asm("v_cvt_pk_bf16_f32 %0, %1, %2" : "=v"(r) : "v"(lo), "v"(hi)); return r; }
;     __device__ __forceinline__ void operator()(const f32x4 (&acc)[2][2][4][2], const Unit& u, int wr, int wc, int fr, int fq) const {
;     ...
;             for (int m = 0; m < 4; ++m) { bf16_t* rowp = O + (size_t)(row0 + ai * HALF + m * 16) * ldc + col0;
; #pragma unroll
;                 for (int bj = 0; bj < 2; ++bj) { f32x4 v0 = acc[ai][bj][m][0], v1 = acc[ai][bj][m][1];
;                     if (ACT == 1) {
; #pragma unroll
;                         for (int j = 0; j < 4; ++j) { const float a = fmaxf(v0[j], 0.f), b = fmaxf(v1[j], 0.f); v0[j] = a * a; v1[j] = b * b; } }
;                     u32x4 w; w.x = cvt_pk_bf16(v0[0], v0[1]); w.y = cvt_pk_bf16(v0[2], v0[3]); w.z = cvt_pk_bf16(v1[0], v1[1]); w.w = cvt_pk_bf16(v1[2], v1[3]);
;                     *(u32x4*)(rowp + bj * HALF) = w; } }
	v_mul_f32_e32 v106, v106, v106
	v_max_f32_e32 v107, 0, v107
	v_max_f32_e32 v108, 0, v108
	v_max_f32_e32 v109, 0, v109
	v_max_f32_e32 v98, v98, v98
	v_lshl_add_u64 v[114:115], v[114:115], 0, v[182:183]
	v_mul_f32_e32 v110, v110, v110
	v_mul_f32_e32 v107, v107, v107
	v_mul_f32_e32 v108, v108, v108
	v_mul_f32_e32 v109, v109, v109
	v_cvt_pk_bf16_f32 v106, v110, v106
	v_max_f32_e32 v98, 0, v98
	v_max_f32_e32 v99, v99, v99
	v_max_f32_e32 v100, v100, v100
	v_cvt_pk_bf16_f32 v107, v107, v108
	v_cvt_pk_bf16_f32 v108, v116, v111
	v_cvt_pk_bf16_f32 v109, v112, v109
	global_store_dwordx4 v[114:115], v[106:109], off
	v_max_f32_e32 v99, 0, v99
	v_max_f32_e32 v100, 0, v100
	v_mul_f32_e32 v106, v98, v98
	v_max_f32_e32 v98, v103, v103
	v_max_f32_e32 v102, v102, v102
	v_max_f32_e32 v98, 0, v98
	v_mul_f32_e32 v103, v99, v99
	v_max_f32_e32 v99, v104, v104
	v_mul_f32_e32 v104, v100, v100
	v_max_f32_e32 v100, v105, v105
	v_max_f32_e32 v101, v101, v101
	v_max_f32_e32 v102, 0, v102
	v_mul_f32_e32 v98, v98, v98
	v_max_f32_e32 v99, 0, v99
	v_max_f32_e32 v100, 0, v100
	v_max_f32_e32 v101, 0, v101
	v_mul_f32_e32 v102, v102, v102
	v_mul_f32_e32 v99, v99, v99
	v_mul_f32_e32 v100, v100, v100
	v_mul_f32_e32 v101, v101, v101
	v_cvt_pk_bf16_f32 v98, v102, v98
	v_max_f32_e32 v90, v90, v90
	v_cvt_pk_bf16_f32 v99, v99, v100
	v_cvt_pk_bf16_f32 v100, v106, v103
	v_cvt_pk_bf16_f32 v101, v104, v101
	global_store_dwordx4 v[114:115], v[98:101], off offset:256
	v_max_f32_e32 v90, 0, v90
	v_max_f32_e32 v91, v91, v91
	v_or_b32_e32 v98, 32, v158
	v_max_f32_e32 v92, v92, v92
	v_ashrrev_i32_e32 v99, 31, v98
	v_mul_f32_e32 v100, v90, v90
	v_max_f32_e32 v90, v95, v95
	v_max_f32_e32 v91, 0, v91
	v_max_f32_e32 v92, 0, v92
	v_lshlrev_b64 v[98:99], 14, v[98:99]
	v_max_f32_e32 v94, v94, v94
	v_max_f32_e32 v90, 0, v90
	v_mul_f32_e32 v95, v91, v91
	v_max_f32_e32 v91, v96, v96
	v_mul_f32_e32 v96, v92, v92
	v_max_f32_e32 v92, v97, v97
	v_max_f32_e32 v93, v93, v93
	v_lshl_add_u64 v[98:99], s[78:79], 0, v[98:99]
	v_max_f32_e32 v94, 0, v94
	v_mul_f32_e32 v90, v90, v90
	v_max_f32_e32 v91, 0, v91
	v_max_f32_e32 v92, 0, v92
	v_max_f32_e32 v93, 0, v93
	v_max_f32_e32 v82, v82, v82
	v_lshl_add_u64 v[98:99], v[98:99], 0, v[182:183]
	v_mul_f32_e32 v94, v94, v94
	v_mul_f32_e32 v91, v91, v91
	v_mul_f32_e32 v92, v92, v92
	v_mul_f32_e32 v93, v93, v93
	v_cvt_pk_bf16_f32 v90, v94, v90
	v_max_f32_e32 v82, 0, v82
	v_max_f32_e32 v83, v83, v83
	v_max_f32_e32 v84, v84, v84
	v_cvt_pk_bf16_f32 v91, v91, v92
	v_cvt_pk_bf16_f32 v92, v100, v95
	v_cvt_pk_bf16_f32 v93, v96, v93
	global_store_dwordx4 v[98:99], v[90:93], off
	v_max_f32_e32 v83, 0, v83
	v_max_f32_e32 v84, 0, v84
	v_mul_f32_e32 v90, v82, v82
	v_max_f32_e32 v82, v87, v87
	v_max_f32_e32 v86, v86, v86
	v_max_f32_e32 v82, 0, v82
	v_mul_f32_e32 v87, v83, v83
	v_max_f32_e32 v83, v88, v88
	v_mul_f32_e32 v88, v84, v84
	v_max_f32_e32 v84, v89, v89
	v_max_f32_e32 v85, v85, v85
	v_max_f32_e32 v86, 0, v86
	v_mul_f32_e32 v82, v82, v82
	v_max_f32_e32 v83, 0, v83
	v_max_f32_e32 v84, 0, v84
	v_max_f32_e32 v85, 0, v85
	v_mul_f32_e32 v86, v86, v86
	v_mul_f32_e32 v83, v83, v83
	v_mul_f32_e32 v84, v84, v84
	v_mul_f32_e32 v85, v85, v85
	v_cvt_pk_bf16_f32 v82, v86, v82
	v_max_f32_e32 v74, v74, v74
	v_cvt_pk_bf16_f32 v83, v83, v84
	v_cvt_pk_bf16_f32 v84, v90, v87
	v_cvt_pk_bf16_f32 v85, v88, v85
	global_store_dwordx4 v[98:99], v[82:85], off offset:256
	v_max_f32_e32 v74, 0, v74
	v_max_f32_e32 v75, v75, v75
	v_or_b32_e32 v82, 48, v158
	v_max_f32_e32 v76, v76, v76
	v_ashrrev_i32_e32 v83, 31, v82
	v_mul_f32_e32 v84, v74, v74
	v_max_f32_e32 v74, v79, v79
	v_max_f32_e32 v75, 0, v75
	v_max_f32_e32 v76, 0, v76
	v_lshlrev_b64 v[82:83], 14, v[82:83]
	v_max_f32_e32 v78, v78, v78
	v_max_f32_e32 v74, 0, v74
	v_mul_f32_e32 v79, v75, v75
	v_max_f32_e32 v75, v80, v80
	v_mul_f32_e32 v80, v76, v76
	v_max_f32_e32 v76, v81, v81
	v_max_f32_e32 v77, v77, v77
	v_lshl_add_u64 v[82:83], s[78:79], 0, v[82:83]
	v_max_f32_e32 v78, 0, v78
	v_mul_f32_e32 v74, v74, v74
	v_max_f32_e32 v75, 0, v75
	v_max_f32_e32 v76, 0, v76
	v_max_f32_e32 v77, 0, v77
	v_max_f32_e32 v66, v66, v66
	v_max_f32_e32 v67, v67, v67
	v_max_f32_e32 v68, v68, v68
	v_lshl_add_u64 v[82:83], v[82:83], 0, v[182:183]
	v_mul_f32_e32 v78, v78, v78
	v_mul_f32_e32 v75, v75, v75
	v_mul_f32_e32 v76, v76, v76
	v_mul_f32_e32 v77, v77, v77
	v_cvt_pk_bf16_f32 v74, v78, v74
	v_max_f32_e32 v66, 0, v66
	v_max_f32_e32 v67, 0, v67
	v_max_f32_e32 v68, 0, v68
	v_cvt_pk_bf16_f32 v75, v75, v76
	v_cvt_pk_bf16_f32 v76, v84, v79
	v_cvt_pk_bf16_f32 v77, v80, v77
	global_store_dwordx4 v[82:83], v[74:77], off
	v_max_f32_e32 v69, v69, v69
	v_max_f32_e32 v70, v70, v70
	v_mul_f32_e32 v74, v66, v66
	v_max_f32_e32 v66, v71, v71
	v_mul_f32_e32 v71, v67, v67
	v_max_f32_e32 v67, v72, v72
	v_mul_f32_e32 v72, v68, v68
	v_max_f32_e32 v68, v73, v73
	v_max_f32_e32 v67, 0, v67
	v_max_f32_e32 v68, 0, v68
	v_max_f32_e32 v66, 0, v66
	v_mul_f32_e32 v67, v67, v67
	v_max_f32_e32 v69, 0, v69
	v_mul_f32_e32 v68, v68, v68
	v_max_f32_e32 v58, v58, v58
	v_max_f32_e32 v70, 0, v70
	v_mul_f32_e32 v66, v66, v66
	v_mul_f32_e32 v69, v69, v69
	v_cvt_pk_bf16_f32 v67, v67, v68
	v_cvt_pk_bf16_f32 v68, v74, v71
	v_max_f32_e32 v58, 0, v58
	v_max_f32_e32 v59, v59, v59
	v_max_f32_e32 v60, v60, v60
	v_mul_f32_e32 v70, v70, v70
	v_cvt_pk_bf16_f32 v66, v70, v66
	v_cvt_pk_bf16_f32 v69, v72, v69
	global_store_dwordx4 v[82:83], v[66:69], off offset:256
	v_max_f32_e32 v62, v62, v62
	v_max_f32_e32 v59, 0, v59
	v_mul_f32_e32 v68, v58, v58
	v_max_f32_e32 v58, v63, v63
	v_max_f32_e32 v60, 0, v60
	v_max_f32_e32 v62, 0, v62
	v_max_f32_e32 v58, 0, v58
	v_mul_f32_e32 v63, v59, v59
	v_max_f32_e32 v59, v64, v64
; __device__ __forceinline__ unsigned cvt_pk_bf16(float lo, float hi) { unsigned r; asm("v_cvt_pk_bf16_f32 %0, %1, %2" : "=v"(r) : "v"(lo), "v"(hi)); return r; }
;     __device__ __forceinline__ void operator()(const f32x4 (&acc)[2][2][4][2], const Unit& u, int wr, int wc, int fr, int fq) const {
;     ...
;                 for (int bj = 0; bj < 2; ++bj) { f32x4 v0 = acc[ai][bj][m][0], v1 = acc[ai][bj][m][1];
;                     if (ACT == 1) {
; #pragma unroll
;                         for (int j = 0; j < 4; ++j) { const float a = fmaxf(v0[j], 0.f), b = fmaxf(v1[j], 0.f); v0[j] = a * a; v1[j] = b * b; } }
;                     u32x4 w; w.x = cvt_pk_bf16(v0[0], v0[1]); w.y = cvt_pk_bf16(v0[2], v0[3]); w.z = cvt_pk_bf16(v1[0], v1[1]); w.w = cvt_pk_bf16(v1[2], v1[3]);
;                     *(u32x4*)(rowp + bj * HALF) = w; } }
	v_mul_f32_e32 v64, v60, v60
	v_max_f32_e32 v60, v65, v65
	v_mul_f32_e32 v62, v62, v62
	v_mul_f32_e32 v58, v58, v58
	v_max_f32_e32 v59, 0, v59
	v_max_f32_e32 v60, 0, v60
	v_max_f32_e32 v61, v61, v61
	s_mov_b32 s1, 0x200000
	v_mul_f32_e32 v59, v59, v59
	v_max_f32_e32 v61, 0, v61
	v_mul_f32_e32 v60, v60, v60
	v_cvt_pk_bf16_f32 v58, v62, v58
	v_add_co_u32_e32 v62, vcc, s1, v152
	v_max_f32_e32 v50, v50, v50
	v_max_f32_e32 v51, v51, v51
	v_max_f32_e32 v52, v52, v52
	v_mul_f32_e32 v61, v61, v61
	v_cvt_pk_bf16_f32 v59, v59, v60
	v_cvt_pk_bf16_f32 v60, v68, v63
	v_addc_co_u32_e32 v63, vcc, 0, v153, vcc
	v_max_f32_e32 v50, 0, v50
	v_max_f32_e32 v51, 0, v51
	v_max_f32_e32 v52, 0, v52
	v_cvt_pk_bf16_f32 v61, v64, v61
	global_store_dwordx4 v[62:63], v[58:61], off
	v_max_f32_e32 v53, v53, v53
	s_mov_b64 s[12:13], 0x200000
	v_mul_f32_e32 v58, v50, v50
	v_max_f32_e32 v50, v55, v55
	v_mul_f32_e32 v55, v51, v51
	v_max_f32_e32 v51, v56, v56
	v_mul_f32_e32 v56, v52, v52
	v_max_f32_e32 v52, v57, v57
	v_max_f32_e32 v51, 0, v51
	v_max_f32_e32 v52, 0, v52
	v_max_f32_e32 v54, v54, v54
	v_max_f32_e32 v50, 0, v50
	v_mul_f32_e32 v51, v51, v51
	v_max_f32_e32 v53, 0, v53
	v_mul_f32_e32 v52, v52, v52
	v_max_f32_e32 v42, v42, v42
	v_lshl_add_u64 v[66:67], v[152:153], 0, s[12:13]
	v_max_f32_e32 v54, 0, v54
	v_mul_f32_e32 v50, v50, v50
	v_mul_f32_e32 v53, v53, v53
	v_cvt_pk_bf16_f32 v51, v51, v52
	v_cvt_pk_bf16_f32 v52, v58, v55
	v_max_f32_e32 v42, 0, v42
	v_max_f32_e32 v43, v43, v43
	v_max_f32_e32 v44, v44, v44
	v_mul_f32_e32 v54, v54, v54
	v_cvt_pk_bf16_f32 v50, v54, v50
	v_cvt_pk_bf16_f32 v53, v56, v53
	global_store_dwordx4 v[66:67], v[50:53], off offset:256
	v_max_f32_e32 v46, v46, v46
	v_max_f32_e32 v43, 0, v43
	v_mul_f32_e32 v52, v42, v42
	v_max_f32_e32 v42, v47, v47
	v_max_f32_e32 v44, 0, v44
	v_max_f32_e32 v46, 0, v46
	v_max_f32_e32 v42, 0, v42
	v_mul_f32_e32 v47, v43, v43
	v_max_f32_e32 v43, v48, v48
	v_mul_f32_e32 v48, v44, v44
	v_max_f32_e32 v44, v49, v49
	v_mul_f32_e32 v46, v46, v46
	v_mul_f32_e32 v42, v42, v42
	v_max_f32_e32 v43, 0, v43
	v_max_f32_e32 v44, 0, v44
	v_max_f32_e32 v45, v45, v45
	s_mov_b32 s1, 0x240000
	v_mul_f32_e32 v43, v43, v43
	v_max_f32_e32 v45, 0, v45
	v_mul_f32_e32 v44, v44, v44
	v_cvt_pk_bf16_f32 v42, v46, v42
	v_add_co_u32_e32 v46, vcc, s1, v152
	v_max_f32_e32 v34, v34, v34
	v_max_f32_e32 v35, v35, v35
	v_max_f32_e32 v36, v36, v36
	v_mul_f32_e32 v45, v45, v45
	v_cvt_pk_bf16_f32 v43, v43, v44
	v_cvt_pk_bf16_f32 v44, v52, v47
	v_addc_co_u32_e32 v47, vcc, 0, v153, vcc
	v_max_f32_e32 v34, 0, v34
	v_max_f32_e32 v35, 0, v35
	v_max_f32_e32 v36, 0, v36
	v_cvt_pk_bf16_f32 v45, v48, v45
	global_store_dwordx4 v[46:47], v[42:45], off
	v_max_f32_e32 v37, v37, v37
	s_mov_b64 s[12:13], 0x240000
	v_mul_f32_e32 v42, v34, v34
	v_max_f32_e32 v34, v39, v39
	v_mul_f32_e32 v39, v35, v35
	v_max_f32_e32 v35, v40, v40
	v_mul_f32_e32 v40, v36, v36
	v_max_f32_e32 v36, v41, v41
	v_max_f32_e32 v35, 0, v35
	v_max_f32_e32 v36, 0, v36
	v_max_f32_e32 v38, v38, v38
	v_max_f32_e32 v34, 0, v34
	v_mul_f32_e32 v35, v35, v35
	v_max_f32_e32 v37, 0, v37
	v_mul_f32_e32 v36, v36, v36
	v_max_f32_e32 v26, v26, v26
	v_lshl_add_u64 v[50:51], v[152:153], 0, s[12:13]
	v_max_f32_e32 v38, 0, v38
	v_mul_f32_e32 v34, v34, v34
	v_mul_f32_e32 v37, v37, v37
	v_cvt_pk_bf16_f32 v35, v35, v36
	v_cvt_pk_bf16_f32 v36, v42, v39
	v_max_f32_e32 v26, 0, v26
	v_max_f32_e32 v27, v27, v27
	v_max_f32_e32 v28, v28, v28
	v_mul_f32_e32 v38, v38, v38
	v_cvt_pk_bf16_f32 v34, v38, v34
	v_cvt_pk_bf16_f32 v37, v40, v37
	global_store_dwordx4 v[50:51], v[34:37], off offset:256
	v_max_f32_e32 v30, v30, v30
	v_max_f32_e32 v27, 0, v27
	v_mul_f32_e32 v36, v26, v26
	v_max_f32_e32 v26, v31, v31
	v_max_f32_e32 v28, 0, v28
; __device__ __forceinline__ unsigned cvt_pk_bf16(float lo, float hi) { unsigned r; asm("v_cvt_pk_bf16_f32 %0, %1, %2" : "=v"(r) : "v"(lo), "v"(hi)); return r; }
; #define PG8_WAIT_V(n) asm volatile("s_waitcnt vmcnt(" #n ")" ::: "memory")
; #define PG8_BAR __builtin_amdgcn_s_barrier()
;     __device__ __forceinline__ void operator()(const f32x4 (&acc)[2][2][4][2], const Unit& u, int wr, int wc, int fr, int fq) const {
;     ...
;                 for (int bj = 0; bj < 2; ++bj) { f32x4 v0 = acc[ai][bj][m][0], v1 = acc[ai][bj][m][1];
;                     if (ACT == 1) {
; #pragma unroll
;                         for (int j = 0; j < 4; ++j) { const float a = fmaxf(v0[j], 0.f), b = fmaxf(v1[j], 0.f); v0[j] = a * a; v1[j] = b * b; } }
;                     u32x4 w; w.x = cvt_pk_bf16(v0[0], v0[1]); w.y = cvt_pk_bf16(v0[2], v0[3]); w.z = cvt_pk_bf16(v1[0], v1[1]); w.w = cvt_pk_bf16(v1[2], v1[3]);
;                     *(u32x4*)(rowp + bj * HALF) = w; } }
; template <class Epi, bool SEG>
; __device__ __forceinline__ void gemm_phase(LAS unsigned char* lds, const Gemm g, const StaticOrder& S, const Epi& E) {
;     ...
;         E(acc, cur, wr, wc, fr, fq);
;         if (!has_next) break;
; #pragma unroll
;         for (int a = 0; a < 2; ++a)
; #pragma unroll
;             for (int b = 0; b < 2; ++b)
; #pragma unroll
;                 for (int m = 0; m < 4; ++m)
; #pragma unroll
;                     for (int n = 0; n < 2; ++n) acc[a][b][m][n] = (f32x4){0.f, 0.f, 0.f, 0.f};
;         cur = nxt; cA = nA; cB = nB; ++ui;
;     }
;     PG8_WAIT_V(0);
;     if (wr == 0) PG8_BAR;
;     PG8_BAR;
	v_max_f32_e32 v30, 0, v30
	v_max_f32_e32 v26, 0, v26
	v_mul_f32_e32 v31, v27, v27
	v_max_f32_e32 v27, v32, v32
	v_mul_f32_e32 v32, v28, v28
	v_max_f32_e32 v28, v33, v33
	v_mul_f32_e32 v30, v30, v30
	v_mul_f32_e32 v26, v26, v26
	v_max_f32_e32 v27, 0, v27
	v_max_f32_e32 v28, 0, v28
	v_max_f32_e32 v29, v29, v29
	s_mov_b32 s1, 0x280000
	v_mul_f32_e32 v27, v27, v27
	v_max_f32_e32 v29, 0, v29
	v_mul_f32_e32 v28, v28, v28
	v_cvt_pk_bf16_f32 v26, v30, v26
	v_add_co_u32_e32 v30, vcc, s1, v152
	v_max_f32_e32 v18, v18, v18
	v_max_f32_e32 v19, v19, v19
	v_max_f32_e32 v20, v20, v20
	v_mul_f32_e32 v29, v29, v29
	v_cvt_pk_bf16_f32 v27, v27, v28
	v_cvt_pk_bf16_f32 v28, v36, v31
	v_addc_co_u32_e32 v31, vcc, 0, v153, vcc
	v_max_f32_e32 v18, 0, v18
	v_max_f32_e32 v19, 0, v19
	v_max_f32_e32 v20, 0, v20
	v_cvt_pk_bf16_f32 v29, v32, v29
	global_store_dwordx4 v[30:31], v[26:29], off
	v_max_f32_e32 v21, v21, v21
	s_mov_b64 s[12:13], 0x280000
	v_mul_f32_e32 v26, v18, v18
	v_max_f32_e32 v18, v23, v23
	v_mul_f32_e32 v23, v19, v19
	v_max_f32_e32 v19, v24, v24
	v_mul_f32_e32 v24, v20, v20
	v_max_f32_e32 v20, v25, v25
	v_max_f32_e32 v19, 0, v19
	v_max_f32_e32 v20, 0, v20
	v_max_f32_e32 v22, v22, v22
	v_max_f32_e32 v18, 0, v18
	v_mul_f32_e32 v19, v19, v19
	v_max_f32_e32 v21, 0, v21
	v_mul_f32_e32 v20, v20, v20
	v_max_f32_e32 v10, v10, v10
	v_lshl_add_u64 v[34:35], v[152:153], 0, s[12:13]
	v_max_f32_e32 v22, 0, v22
	v_mul_f32_e32 v18, v18, v18
	v_mul_f32_e32 v21, v21, v21
	v_cvt_pk_bf16_f32 v19, v19, v20
	v_cvt_pk_bf16_f32 v20, v26, v23
	v_max_f32_e32 v10, 0, v10
	v_max_f32_e32 v11, v11, v11
	v_max_f32_e32 v12, v12, v12
	v_mul_f32_e32 v22, v22, v22
	v_cvt_pk_bf16_f32 v18, v22, v18
	v_cvt_pk_bf16_f32 v21, v24, v21
	global_store_dwordx4 v[34:35], v[18:21], off offset:256
	v_max_f32_e32 v14, v14, v14
	v_max_f32_e32 v11, 0, v11
	v_mul_f32_e32 v20, v10, v10
	v_max_f32_e32 v10, v15, v15
	v_max_f32_e32 v12, 0, v12
	v_max_f32_e32 v14, 0, v14
	v_max_f32_e32 v10, 0, v10
	v_mul_f32_e32 v15, v11, v11
	v_max_f32_e32 v11, v16, v16
	v_mul_f32_e32 v16, v12, v12
	v_max_f32_e32 v12, v17, v17
	v_mul_f32_e32 v14, v14, v14
	v_mul_f32_e32 v10, v10, v10
	v_max_f32_e32 v11, 0, v11
	v_max_f32_e32 v12, 0, v12
	v_max_f32_e32 v13, v13, v13
	s_mov_b32 s1, 0x2c0000
	v_mul_f32_e32 v11, v11, v11
	v_max_f32_e32 v13, 0, v13
	v_mul_f32_e32 v12, v12, v12
	v_cvt_pk_bf16_f32 v10, v14, v10
	v_add_co_u32_e32 v14, vcc, s1, v152
	v_max_f32_e32 v2, v2, v2
	v_max_f32_e32 v3, v3, v3
	v_max_f32_e32 v4, v4, v4
	v_mul_f32_e32 v13, v13, v13
	v_cvt_pk_bf16_f32 v11, v11, v12
	v_cvt_pk_bf16_f32 v12, v20, v15
	v_addc_co_u32_e32 v15, vcc, 0, v153, vcc
	v_max_f32_e32 v2, 0, v2
	v_max_f32_e32 v3, 0, v3
	v_max_f32_e32 v4, 0, v4
	v_cvt_pk_bf16_f32 v13, v16, v13
	global_store_dwordx4 v[14:15], v[10:13], off
	v_max_f32_e32 v5, v5, v5
	s_mov_b64 s[12:13], 0x2c0000
	v_mul_f32_e32 v10, v2, v2
	v_max_f32_e32 v2, v7, v7
	v_mul_f32_e32 v7, v3, v3
	v_max_f32_e32 v3, v8, v8
	v_mul_f32_e32 v8, v4, v4
	v_max_f32_e32 v4, v9, v9
	v_max_f32_e32 v6, v6, v6
	v_max_f32_e32 v2, 0, v2
	v_max_f32_e32 v3, 0, v3
	v_max_f32_e32 v4, 0, v4
	v_max_f32_e32 v5, 0, v5
	v_lshl_add_u64 v[18:19], v[152:153], 0, s[12:13]
	v_max_f32_e32 v6, 0, v6
	v_mul_f32_e32 v2, v2, v2
	v_mul_f32_e32 v3, v3, v3
	v_mul_f32_e32 v4, v4, v4
	v_mul_f32_e32 v5, v5, v5
	s_and_b64 vcc, exec, s[2:3]
	s_mov_b32 s31, s0
	s_mov_b32 s10, s4
	s_mov_b64 s[14:15], s[8:9]
	s_mov_b64 s[12:13], s[6:7]
	v_mul_f32_e32 v6, v6, v6
	v_cvt_pk_bf16_f32 v2, v6, v2
	v_cvt_pk_bf16_f32 v3, v3, v4
	v_cvt_pk_bf16_f32 v4, v10, v7
	v_cvt_pk_bf16_f32 v5, v8, v5
	global_store_dwordx4 v[18:19], v[2:5], off offset:256
	s_cbranch_vccz .LBB0_62
	s_waitcnt vmcnt(0)
	s_cmpk_gt_u32 s21, 0xff
	s_cbranch_scc1 .LBB0_73
	s_barrier

; #define PG8_STAGE(bufoff, gbase, voff) do { _Pragma("unroll") for (int _i = 0; _i < 2; ++_i) \
;         __builtin_amdgcn_global_load_lds((const unsigned*)((const char*)(gbase) + (voff)[_i]), (LAS unsigned*)(lds + (bufoff) + ldsw + _i * 8192), 16, 0, 0); } while (0)
; #define PG8_LDA(dst, b, h) do { _Pragma("unroll") for (int m = 0; m < 4; ++m) _Pragma("unroll") for (int k = 0; k < 2; ++k) dst[m][k] = *(const LAS bf16x8*)(lds + PG8_SA(b, h) + aoff + m * 2048 + k * 1024); } while (0)
; #define PG8_LDB(dst, b, h) do { _Pragma("unroll") for (int n = 0; n < 2; ++n) _Pragma("unroll") for (int k = 0; k < 2; ++k) dst[n][k] = *(const LAS bf16x8*)(lds + PG8_SB(b, h) + boff + n * 2048 + k * 1024); } while (0)
; #define PG8_MMA(ai, bj, At, Bt) do { __builtin_amdgcn_s_setprio(1); _Pragma("unroll") for (int m = 0; m < 4; ++m) _Pragma("unroll") for (int n = 0; n < 2; ++n) _Pragma("unroll") for (int k = 0; k < 2; ++k) \
;         acc[ai][bj][m][n] = __builtin_amdgcn_mfma_f32_16x16x32_bf16(Bt[n][k], At[m][k], acc[ai][bj][m][n], 0, 0, 0); __builtin_amdgcn_s_setprio(0); } while (0)
; #define PG8_WAIT_L(n) asm volatile("s_waitcnt lgkmcnt(" #n ")" ::: "memory")
; template <bool SEG> __device__ __forceinline__ size_t akoff(int t) {
;     if (!SEG) return (size_t)t * (BK * 2);
;     const int kk = t * BK; const int col = kk < 512 ? kk : (kk < 1280 ? kk + 1024 : kk + 5248); return (size_t)col * 2;
; template <class Epi, bool SEG>
; __device__ __forceinline__ void gemm_phase(LAS unsigned char* lds, const Gemm g, const StaticOrder& S, const Epi& E) {
;     ...
;         for (int t = 0; t < nt; t += 2) {
;             const bool last = (t == nt - 2);
;             const char* a1 = cA + akoff<SEG>(t) + kstep;
;             const char* a2 = last ? nA : cA + akoff<SEG>(t + 2); const char* b2 = last ? nB : cB + (size_t)(t + 2) * kstep;
;             const char* a3 = a2 + kstep; const char* b3 = b2 + kstep;
;             PG8_LDB(B0, 0, 0); PG8_SCHED; PG8_LDA(At, 0, 0); PG8_STAGE(PG8_SA(1, 1), a1 + hstepA, voffA);
;             PG8_WAIT_L(8); PG8_BAR; PG8_WAIT_L(0); PG8_MMA(0, 0, At, B0); PG8_BAR; PG8_SCHED;
;             PG8_LDB(B1, 0, 1); PG8_STAGE(PG8_SB(0, 0), b2, voffB);
;             PG8_BAR; PG8_WAIT_L(0); PG8_MMA(0, 1, At, B1); PG8_BAR;
;             PG8_LDA(At, 0, 1); PG8_STAGE(PG8_SA(0, 0), a2, voffA);
;             PG8_BAR; PG8_WAIT_L(0); PG8_MMA(1, 0, At, B0); PG8_BAR; PG8_SCHED;
.LBB0_102:
	s_cmp_lt_u32 s38, 20
	s_movk_i32 s39, 0x2900
	s_cselect_b32 s39, 0x800, s39
	s_cmp_gt_u32 s38, 7
	s_cselect_b32 s39, s39, 0
	s_add_i32 s39, s0, s39
	s_add_u32 s39, s10, s39
	s_addc_u32 s41, s11, 0
	s_add_u32 s40, s35, s0
	s_addc_u32 s42, s36, s1
	s_add_i32 s43, 0, 0x10000
	v_add_u32_e32 v148, s43, v151
	ds_read_b128 v[154:157], v148
	ds_read_b128 v[180:183], v148 offset:1024
	ds_read_b128 v[184:187], v148 offset:2048
	ds_read_b128 v[188:191], v148 offset:3072
	s_and_b64 s[14:15], exec, s[14:15]
	s_cselect_b32 s15, s5, s42
	s_cselect_b32 s14, s34, s40
	s_add_u32 s40, s39, 0x1d0080
	s_addc_u32 s41, s41, 0
	v_lshl_add_u64 v[148:149], s[40:41], 0, v[142:143]
	s_add_i32 m0, s21, 0xc000
	ds_read_b128 v[198:201], v153
	ds_read_b128 v[202:205], v153 offset:1024
	ds_read_b128 v[206:209], v153 offset:2048
	ds_read_b128 v[210:213], v153 offset:3072
	ds_read_b128 v[214:217], v153 offset:4096
	ds_read_b128 v[218:221], v153 offset:5120
	ds_read_b128 v[222:225], v153 offset:6144
	ds_read_b128 v[226:229], v153 offset:7168
	global_load_lds_dwordx4 v[148:149], off
	v_lshl_add_u64 v[148:149], s[40:41], 0, v[144:145]
	s_add_i32 m0, s21, 0xe000
	s_nop 0
	global_load_lds_dwordx4 v[148:149], off
	s_waitcnt lgkmcnt(8)
	s_barrier
	s_waitcnt lgkmcnt(0)
	v_mfma_f32_16x16x32_bf16 v[126:129], v[154:157], v[198:201], v[126:129]
	v_mfma_f32_16x16x32_bf16 v[122:125], v[184:187], v[198:201], v[122:125]
	v_mfma_f32_16x16x32_bf16 v[118:121], v[154:157], v[206:209], v[118:121]
	v_mfma_f32_16x16x32_bf16 v[110:113], v[184:187], v[206:209], v[110:113]
	v_mfma_f32_16x16x32_bf16 v[102:105], v[154:157], v[214:217], v[102:105]
	v_mfma_f32_16x16x32_bf16 v[94:97], v[184:187], v[214:217], v[94:97]
	v_mfma_f32_16x16x32_bf16 v[82:85], v[154:157], v[222:225], v[82:85]
	v_mfma_f32_16x16x32_bf16 v[74:77], v[184:187], v[222:225], v[74:77]
	v_mfma_f32_16x16x32_bf16 v[126:129], v[180:183], v[202:205], v[126:129]
	v_mfma_f32_16x16x32_bf16 v[122:125], v[188:191], v[202:205], v[122:125]
	v_mfma_f32_16x16x32_bf16 v[118:121], v[180:183], v[210:213], v[118:121]
	v_mfma_f32_16x16x32_bf16 v[110:113], v[188:191], v[210:213], v[110:113]
	v_mfma_f32_16x16x32_bf16 v[102:105], v[180:183], v[218:221], v[102:105]
	v_mfma_f32_16x16x32_bf16 v[94:97], v[188:191], v[218:221], v[94:97]
	v_mfma_f32_16x16x32_bf16 v[82:85], v[180:183], v[226:229], v[82:85]
	v_mfma_f32_16x16x32_bf16 v[74:77], v[188:191], v[226:229], v[74:77]
	s_barrier
	s_add_i32 s39, 0, 0x14000
	v_add_u32_e32 v148, s39, v151
	s_add_i32 s40, s43, s20
	ds_read_b128 v[230:233], v148
	ds_read_b128 v[234:237], v148 offset:1024
	ds_read_b128 v[238:241], v148 offset:2048
	ds_read_b128 v[242:245], v148 offset:3072
	v_lshl_add_u64 v[148:149], s[14:15], 0, v[0:1]
	s_mov_b32 m0, s40
	v_lshl_add_u64 v[158:159], s[14:15], 0, v[146:147]
	global_load_lds_dwordx4 v[148:149], off
	s_add_i32 m0, s40, 0x2000
	s_nop 0
	global_load_lds_dwordx4 v[158:159], off
	s_barrier
	s_waitcnt lgkmcnt(0)
	v_mfma_f32_16x16x32_bf16 v[114:117], v[230:233], v[198:201], v[114:117]
	v_mfma_f32_16x16x32_bf16 v[106:109], v[238:241], v[198:201], v[106:109]
	v_mfma_f32_16x16x32_bf16 v[98:101], v[230:233], v[206:209], v[98:101]
	v_mfma_f32_16x16x32_bf16 v[90:93], v[238:241], v[206:209], v[90:93]
	v_mfma_f32_16x16x32_bf16 v[86:89], v[230:233], v[214:217], v[86:89]
	v_mfma_f32_16x16x32_bf16 v[78:81], v[238:241], v[214:217], v[78:81]
	v_mfma_f32_16x16x32_bf16 v[70:73], v[230:233], v[222:225], v[70:73]
	v_mfma_f32_16x16x32_bf16 v[66:69], v[238:241], v[222:225], v[66:69]
	v_mfma_f32_16x16x32_bf16 v[114:117], v[234:237], v[202:205], v[114:117]
	v_mfma_f32_16x16x32_bf16 v[106:109], v[242:245], v[202:205], v[106:109]
	v_mfma_f32_16x16x32_bf16 v[98:101], v[234:237], v[210:213], v[98:101]
	v_mfma_f32_16x16x32_bf16 v[90:93], v[242:245], v[210:213], v[90:93]
	v_mfma_f32_16x16x32_bf16 v[86:89], v[234:237], v[218:221], v[86:89]
	v_mfma_f32_16x16x32_bf16 v[78:81], v[242:245], v[218:221], v[78:81]
	v_mfma_f32_16x16x32_bf16 v[70:73], v[234:237], v[226:229], v[70:73]
	v_mfma_f32_16x16x32_bf16 v[66:69], v[242:245], v[226:229], v[66:69]
	s_mov_b32 m0, s21
	v_lshl_add_u64 v[192:193], s[12:13], 0, v[142:143]
	s_barrier
	ds_read_b128 v[198:201], v153 offset:16384
	ds_read_b128 v[202:205], v153 offset:17408
	ds_read_b128 v[206:209], v153 offset:18432
	ds_read_b128 v[210:213], v153 offset:19456
	ds_read_b128 v[214:217], v153 offset:20480
	ds_read_b128 v[218:221], v153 offset:21504
	ds_read_b128 v[222:225], v153 offset:22528
	ds_read_b128 v[226:229], v153 offset:23552
	global_load_lds_dwordx4 v[192:193], off
	v_lshl_add_u64 v[246:247], s[12:13], 0, v[144:145]
	s_mov_b32 m0, s23
	s_nop 0
	global_load_lds_dwordx4 v[246:247], off
	s_barrier
	s_waitcnt lgkmcnt(0)
	v_mfma_f32_16x16x32_bf16 v[62:65], v[154:157], v[198:201], v[62:65]
	v_mfma_f32_16x16x32_bf16 v[58:61], v[184:187], v[198:201], v[58:61]
	v_mfma_f32_16x16x32_bf16 v[54:57], v[154:157], v[206:209], v[54:57]
	v_mfma_f32_16x16x32_bf16 v[46:49], v[184:187], v[206:209], v[46:49]
	v_mfma_f32_16x16x32_bf16 v[38:41], v[154:157], v[214:217], v[38:41]
	v_mfma_f32_16x16x32_bf16 v[30:33], v[184:187], v[214:217], v[30:33]
	v_mfma_f32_16x16x32_bf16 v[22:25], v[154:157], v[222:225], v[22:25]
	v_mfma_f32_16x16x32_bf16 v[14:17], v[184:187], v[222:225], v[14:17]
	v_mfma_f32_16x16x32_bf16 v[62:65], v[180:183], v[202:205], v[62:65]
	v_mfma_f32_16x16x32_bf16 v[58:61], v[188:191], v[202:205], v[58:61]
	v_mfma_f32_16x16x32_bf16 v[54:57], v[180:183], v[210:213], v[54:57]
	v_mfma_f32_16x16x32_bf16 v[46:49], v[188:191], v[210:213], v[46:49]
	v_mfma_f32_16x16x32_bf16 v[38:41], v[180:183], v[218:221], v[38:41]
	v_mfma_f32_16x16x32_bf16 v[30:33], v[188:191], v[218:221], v[30:33]
	v_mfma_f32_16x16x32_bf16 v[22:25], v[180:183], v[226:229], v[22:25]
	v_mfma_f32_16x16x32_bf16 v[14:17], v[188:191], v[226:229], v[14:17]
	s_barrier
; #define PG8_STAGE(bufoff, gbase, voff) do { _Pragma("unroll") for (int _i = 0; _i < 2; ++_i) \
;         __builtin_amdgcn_global_load_lds((const unsigned*)((const char*)(gbase) + (voff)[_i]), (LAS unsigned*)(lds + (bufoff) + ldsw + _i * 8192), 16, 0, 0); } while (0)
; #define PG8_LDA(dst, b, h) do { _Pragma("unroll") for (int m = 0; m < 4; ++m) _Pragma("unroll") for (int k = 0; k < 2; ++k) dst[m][k] = *(const LAS bf16x8*)(lds + PG8_SA(b, h) + aoff + m * 2048 + k * 1024); } while (0)
; #define PG8_LDB(dst, b, h) do { _Pragma("unroll") for (int n = 0; n < 2; ++n) _Pragma("unroll") for (int k = 0; k < 2; ++k) dst[n][k] = *(const LAS bf16x8*)(lds + PG8_SB(b, h) + boff + n * 2048 + k * 1024); } while (0)
; #define PG8_MMA(ai, bj, At, Bt) do { __builtin_amdgcn_s_setprio(1); _Pragma("unroll") for (int m = 0; m < 4; ++m) _Pragma("unroll") for (int n = 0; n < 2; ++n) _Pragma("unroll") for (int k = 0; k < 2; ++k) \
;         acc[ai][bj][m][n] = __builtin_amdgcn_mfma_f32_16x16x32_bf16(Bt[n][k], At[m][k], acc[ai][bj][m][n], 0, 0, 0); __builtin_amdgcn_s_setprio(0); } while (0)
; #define PG8_WAIT_V(n) asm volatile("s_waitcnt vmcnt(" #n ")" ::: "memory")
; #define PG8_WAIT_L(n) asm volatile("s_waitcnt lgkmcnt(" #n ")" ::: "memory")
; #define PG8_BAR __builtin_amdgcn_s_barrier()
; #define PG8_SCHED __builtin_amdgcn_sched_barrier(0)
; template <class Epi, bool SEG>
; __device__ __forceinline__ void gemm_phase(LAS unsigned char* lds, const Gemm g, const StaticOrder& S, const Epi& E) {
;     ...
;             PG8_STAGE(PG8_SB(0, 1), b2 + hstepB, voffB);
;             PG8_WAIT_V(6); PG8_BAR; PG8_MMA(1, 1, At, B1); PG8_BAR;
;             PG8_LDB(B0, 1, 0); PG8_SCHED; PG8_LDA(At, 1, 0); PG8_STAGE(PG8_SA(0, 1), a2 + hstepA, voffA);
;             PG8_WAIT_L(8); PG8_BAR; PG8_WAIT_L(0); PG8_MMA(0, 0, At, B0); PG8_BAR; PG8_SCHED;
;             PG8_LDB(B1, 1, 1); PG8_STAGE(PG8_SB(1, 0), b3, voffB);
;             PG8_BAR; PG8_WAIT_L(0); PG8_MMA(0, 1, At, B1); PG8_BAR;
	s_add_u32 s40, s14, 0x80000
	s_addc_u32 s41, s15, 0
	s_add_i32 s39, s39, s20
	v_lshl_add_u64 v[154:155], s[40:41], 0, v[0:1]
	s_mov_b32 m0, s39
	s_nop 0
	global_load_lds_dwordx4 v[154:155], off
	v_lshl_add_u64 v[154:155], s[40:41], 0, v[146:147]
	s_add_i32 m0, s39, 0x2000
	s_nop 0
	global_load_lds_dwordx4 v[154:155], off
	s_waitcnt vmcnt(6)
	s_barrier
	v_mfma_f32_16x16x32_bf16 v[50:53], v[230:233], v[198:201], v[50:53]
	v_mfma_f32_16x16x32_bf16 v[42:45], v[238:241], v[198:201], v[42:45]
	v_mfma_f32_16x16x32_bf16 v[34:37], v[230:233], v[206:209], v[34:37]
	v_mfma_f32_16x16x32_bf16 v[26:29], v[238:241], v[206:209], v[26:29]
	v_mfma_f32_16x16x32_bf16 v[18:21], v[230:233], v[214:217], v[18:21]
	v_mfma_f32_16x16x32_bf16 v[10:13], v[238:241], v[214:217], v[10:13]
	v_mfma_f32_16x16x32_bf16 v[6:9], v[230:233], v[222:225], v[6:9]
	v_mfma_f32_16x16x32_bf16 v[2:5], v[238:241], v[222:225], v[2:5]
	v_mfma_f32_16x16x32_bf16 v[50:53], v[234:237], v[202:205], v[50:53]
	v_mfma_f32_16x16x32_bf16 v[42:45], v[242:245], v[202:205], v[42:45]
	v_mfma_f32_16x16x32_bf16 v[34:37], v[234:237], v[210:213], v[34:37]
	v_mfma_f32_16x16x32_bf16 v[26:29], v[242:245], v[210:213], v[26:29]
	v_mfma_f32_16x16x32_bf16 v[18:21], v[234:237], v[218:221], v[18:21]
	v_mfma_f32_16x16x32_bf16 v[10:13], v[242:245], v[218:221], v[10:13]
	v_mfma_f32_16x16x32_bf16 v[6:9], v[234:237], v[226:229], v[6:9]
	v_mfma_f32_16x16x32_bf16 v[2:5], v[242:245], v[226:229], v[2:5]
	s_add_i32 s39, 0, 0x18000
	v_add_u32_e32 v179, s39, v151
	s_barrier
	ds_read_b128 v[154:157], v179
	ds_read_b128 v[180:183], v179 offset:1024
	ds_read_b128 v[184:187], v179 offset:2048
	ds_read_b128 v[188:191], v179 offset:3072
	s_add_u32 s12, s12, 0x1d0000
	s_addc_u32 s13, s13, 0
	s_mov_b32 m0, s24
	v_lshl_add_u64 v[230:231], s[12:13], 0, v[142:143]
	ds_read_b128 v[198:201], v153 offset:32768
	ds_read_b128 v[202:205], v153 offset:33792
	ds_read_b128 v[206:209], v153 offset:34816
	ds_read_b128 v[210:213], v153 offset:35840
	ds_read_b128 v[214:217], v153 offset:36864
	ds_read_b128 v[218:221], v153 offset:37888
	ds_read_b128 v[222:225], v153 offset:38912
	ds_read_b128 v[226:229], v153 offset:39936
	global_load_lds_dwordx4 v[230:231], off
	v_lshl_add_u64 v[230:231], s[12:13], 0, v[144:145]
	s_mov_b32 m0, s25
	s_nop 0
	global_load_lds_dwordx4 v[230:231], off
	s_waitcnt lgkmcnt(8)
	s_barrier
	s_waitcnt lgkmcnt(0)
	v_mfma_f32_16x16x32_bf16 v[126:129], v[154:157], v[198:201], v[126:129]
	v_mfma_f32_16x16x32_bf16 v[122:125], v[184:187], v[198:201], v[122:125]
	v_mfma_f32_16x16x32_bf16 v[118:121], v[154:157], v[206:209], v[118:121]
	v_mfma_f32_16x16x32_bf16 v[110:113], v[184:187], v[206:209], v[110:113]
	v_mfma_f32_16x16x32_bf16 v[102:105], v[154:157], v[214:217], v[102:105]
	v_mfma_f32_16x16x32_bf16 v[94:97], v[184:187], v[214:217], v[94:97]
	v_mfma_f32_16x16x32_bf16 v[82:85], v[154:157], v[222:225], v[82:85]
	v_mfma_f32_16x16x32_bf16 v[74:77], v[184:187], v[222:225], v[74:77]
	v_mfma_f32_16x16x32_bf16 v[126:129], v[180:183], v[202:205], v[126:129]
	v_mfma_f32_16x16x32_bf16 v[122:125], v[188:191], v[202:205], v[122:125]
	v_mfma_f32_16x16x32_bf16 v[118:121], v[180:183], v[210:213], v[118:121]
	v_mfma_f32_16x16x32_bf16 v[110:113], v[188:191], v[210:213], v[110:113]
	v_mfma_f32_16x16x32_bf16 v[102:105], v[180:183], v[218:221], v[102:105]
	v_mfma_f32_16x16x32_bf16 v[94:97], v[188:191], v[218:221], v[94:97]
	v_mfma_f32_16x16x32_bf16 v[82:85], v[180:183], v[226:229], v[82:85]
	v_mfma_f32_16x16x32_bf16 v[74:77], v[188:191], v[226:229], v[74:77]
	s_barrier
	s_add_i32 s40, 0, 0x1c000
	s_add_i32 s12, s39, s20
	v_add_u32_e32 v179, s40, v151
	v_lshl_add_u64 v[148:149], v[148:149], 0, s[96:97]
	s_mov_b32 m0, s12
	ds_read_b128 v[230:233], v179
	ds_read_b128 v[234:237], v179 offset:1024
	ds_read_b128 v[238:241], v179 offset:2048
	ds_read_b128 v[242:245], v179 offset:3072
	global_load_lds_dwordx4 v[148:149], off
	v_lshl_add_u64 v[148:149], v[158:159], 0, s[96:97]
	s_add_i32 m0, s12, 0x2000
	s_nop 0
	global_load_lds_dwordx4 v[148:149], off
	s_barrier
; #define PG8_STAGE(bufoff, gbase, voff) do { _Pragma("unroll") for (int _i = 0; _i < 2; ++_i) \
;         __builtin_amdgcn_global_load_lds((const unsigned*)((const char*)(gbase) + (voff)[_i]), (LAS unsigned*)(lds + (bufoff) + ldsw + _i * 8192), 16, 0, 0); } while (0)
; #define PG8_LDA(dst, b, h) do { _Pragma("unroll") for (int m = 0; m < 4; ++m) _Pragma("unroll") for (int k = 0; k < 2; ++k) dst[m][k] = *(const LAS bf16x8*)(lds + PG8_SA(b, h) + aoff + m * 2048 + k * 1024); } while (0)
; #define PG8_MMA(ai, bj, At, Bt) do { __builtin_amdgcn_s_setprio(1); _Pragma("unroll") for (int m = 0; m < 4; ++m) _Pragma("unroll") for (int n = 0; n < 2; ++n) _Pragma("unroll") for (int k = 0; k < 2; ++k) \
;         acc[ai][bj][m][n] = __builtin_amdgcn_mfma_f32_16x16x32_bf16(Bt[n][k], At[m][k], acc[ai][bj][m][n], 0, 0, 0); __builtin_amdgcn_s_setprio(0); } while (0)
; #define PG8_WAIT_V(n) asm volatile("s_waitcnt vmcnt(" #n ")" ::: "memory")
; #define PG8_WAIT_L(n) asm volatile("s_waitcnt lgkmcnt(" #n ")" ::: "memory")
; #define PG8_BAR __builtin_amdgcn_s_barrier()
; #define PG8_SCHED __builtin_amdgcn_sched_barrier(0)
; template <class Epi, bool SEG>
; __device__ __forceinline__ void gemm_phase(LAS unsigned char* lds, const Gemm g, const StaticOrder& S, const Epi& E) {
;     ...
;             PG8_BAR; PG8_WAIT_L(0); PG8_MMA(0, 1, At, B1); PG8_BAR;
;             PG8_LDA(At, 1, 1); PG8_STAGE(PG8_SA(1, 0), a3, voffA);
;             PG8_BAR; PG8_WAIT_L(0); PG8_MMA(1, 0, At, B0); PG8_BAR; PG8_SCHED;
;             PG8_STAGE(PG8_SB(1, 1), b3 + hstepB, voffB);
;             PG8_WAIT_V(6); PG8_BAR; PG8_MMA(1, 1, At, B1); PG8_BAR;
;         }
	s_waitcnt lgkmcnt(0)
	v_mfma_f32_16x16x32_bf16 v[114:117], v[230:233], v[198:201], v[114:117]
	v_mfma_f32_16x16x32_bf16 v[106:109], v[238:241], v[198:201], v[106:109]
	v_mfma_f32_16x16x32_bf16 v[98:101], v[230:233], v[206:209], v[98:101]
	v_mfma_f32_16x16x32_bf16 v[90:93], v[238:241], v[206:209], v[90:93]
	v_mfma_f32_16x16x32_bf16 v[86:89], v[230:233], v[214:217], v[86:89]
	v_mfma_f32_16x16x32_bf16 v[78:81], v[238:241], v[214:217], v[78:81]
	v_mfma_f32_16x16x32_bf16 v[70:73], v[230:233], v[222:225], v[70:73]
	v_mfma_f32_16x16x32_bf16 v[66:69], v[238:241], v[222:225], v[66:69]
	v_mfma_f32_16x16x32_bf16 v[114:117], v[234:237], v[202:205], v[114:117]
	v_mfma_f32_16x16x32_bf16 v[106:109], v[242:245], v[202:205], v[106:109]
	v_mfma_f32_16x16x32_bf16 v[98:101], v[234:237], v[210:213], v[98:101]
	v_mfma_f32_16x16x32_bf16 v[90:93], v[242:245], v[210:213], v[90:93]
	v_mfma_f32_16x16x32_bf16 v[86:89], v[234:237], v[218:221], v[86:89]
	v_mfma_f32_16x16x32_bf16 v[78:81], v[242:245], v[218:221], v[78:81]
	v_mfma_f32_16x16x32_bf16 v[70:73], v[234:237], v[226:229], v[70:73]
	v_mfma_f32_16x16x32_bf16 v[66:69], v[242:245], v[226:229], v[66:69]
	s_mov_b32 m0, s26
	v_lshl_add_u64 v[148:149], v[192:193], 0, s[96:97]
	s_barrier
	ds_read_b128 v[198:201], v153 offset:49152
	ds_read_b128 v[202:205], v153 offset:50176
	ds_read_b128 v[206:209], v153 offset:51200
	ds_read_b128 v[210:213], v153 offset:52224
	ds_read_b128 v[214:217], v153 offset:53248
	ds_read_b128 v[218:221], v153 offset:54272
	ds_read_b128 v[222:225], v153 offset:55296
	ds_read_b128 v[226:229], v153 offset:56320
	global_load_lds_dwordx4 v[148:149], off
	v_lshl_add_u64 v[148:149], v[246:247], 0, s[96:97]
	s_mov_b32 m0, s27
	s_nop 0
	global_load_lds_dwordx4 v[148:149], off
	s_barrier
	s_waitcnt lgkmcnt(0)
	v_mfma_f32_16x16x32_bf16 v[62:65], v[154:157], v[198:201], v[62:65]
	v_mfma_f32_16x16x32_bf16 v[58:61], v[184:187], v[198:201], v[58:61]
	v_mfma_f32_16x16x32_bf16 v[54:57], v[154:157], v[206:209], v[54:57]
	v_mfma_f32_16x16x32_bf16 v[46:49], v[184:187], v[206:209], v[46:49]
	v_mfma_f32_16x16x32_bf16 v[38:41], v[154:157], v[214:217], v[38:41]
	v_mfma_f32_16x16x32_bf16 v[30:33], v[184:187], v[214:217], v[30:33]
	v_mfma_f32_16x16x32_bf16 v[22:25], v[154:157], v[222:225], v[22:25]
	v_mfma_f32_16x16x32_bf16 v[14:17], v[184:187], v[222:225], v[14:17]
	v_mfma_f32_16x16x32_bf16 v[62:65], v[180:183], v[202:205], v[62:65]
	v_mfma_f32_16x16x32_bf16 v[58:61], v[188:191], v[202:205], v[58:61]
	v_mfma_f32_16x16x32_bf16 v[54:57], v[180:183], v[210:213], v[54:57]
	v_mfma_f32_16x16x32_bf16 v[46:49], v[188:191], v[210:213], v[46:49]
	v_mfma_f32_16x16x32_bf16 v[38:41], v[180:183], v[218:221], v[38:41]
	v_mfma_f32_16x16x32_bf16 v[30:33], v[188:191], v[218:221], v[30:33]
	v_mfma_f32_16x16x32_bf16 v[22:25], v[180:183], v[226:229], v[22:25]
	v_mfma_f32_16x16x32_bf16 v[14:17], v[188:191], v[226:229], v[14:17]
	s_barrier
	s_add_u32 s12, s14, 0x80080
	s_addc_u32 s13, s15, 0
	s_add_i32 s14, s40, s20
	v_lshl_add_u64 v[148:149], s[12:13], 0, v[0:1]
	s_mov_b32 m0, s14
	s_nop 0
	global_load_lds_dwordx4 v[148:149], off
	v_lshl_add_u64 v[148:149], s[12:13], 0, v[146:147]
	s_add_i32 m0, s14, 0x2000
	s_nop 0
	global_load_lds_dwordx4 v[148:149], off
	s_waitcnt vmcnt(6)
	s_barrier
	v_mfma_f32_16x16x32_bf16 v[50:53], v[230:233], v[198:201], v[50:53]
	v_mfma_f32_16x16x32_bf16 v[42:45], v[238:241], v[198:201], v[42:45]
	v_mfma_f32_16x16x32_bf16 v[34:37], v[230:233], v[206:209], v[34:37]
	v_mfma_f32_16x16x32_bf16 v[26:29], v[238:241], v[206:209], v[26:29]
	v_mfma_f32_16x16x32_bf16 v[18:21], v[230:233], v[214:217], v[18:21]
	v_mfma_f32_16x16x32_bf16 v[10:13], v[238:241], v[214:217], v[10:13]
	v_mfma_f32_16x16x32_bf16 v[6:9], v[230:233], v[222:225], v[6:9]
	v_mfma_f32_16x16x32_bf16 v[2:5], v[238:241], v[222:225], v[2:5]
	v_mfma_f32_16x16x32_bf16 v[50:53], v[234:237], v[202:205], v[50:53]
	v_mfma_f32_16x16x32_bf16 v[42:45], v[242:245], v[202:205], v[42:45]
	v_mfma_f32_16x16x32_bf16 v[34:37], v[234:237], v[210:213], v[34:37]
	v_mfma_f32_16x16x32_bf16 v[26:29], v[242:245], v[210:213], v[26:29]
	v_mfma_f32_16x16x32_bf16 v[18:21], v[234:237], v[218:221], v[18:21]
	v_mfma_f32_16x16x32_bf16 v[10:13], v[242:245], v[218:221], v[10:13]
	v_mfma_f32_16x16x32_bf16 v[6:9], v[234:237], v[226:229], v[6:9]
	v_mfma_f32_16x16x32_bf16 v[2:5], v[242:245], v[226:229], v[2:5]
	s_add_i32 s12, s38, 2
	s_addk_i32 s37, 0x80
	s_add_u32 s0, s0, 0x100
	s_addc_u32 s1, s1, 0
	s_cmp_gt_u32 s38, 29
	s_mov_b32 s38, s12
	s_barrier
	s_cbranch_scc1 .LBB0_92

; #define PG8_STAGE(bufoff, gbase, voff) do { _Pragma("unroll") for (int _i = 0; _i < 2; ++_i) \
;         __builtin_amdgcn_global_load_lds((const unsigned*)((const char*)(gbase) + (voff)[_i]), (LAS unsigned*)(lds + (bufoff) + ldsw + _i * 8192), 16, 0, 0); } while (0)
; #define PG8_LDA(dst, b, h) do { _Pragma("unroll") for (int m = 0; m < 4; ++m) _Pragma("unroll") for (int k = 0; k < 2; ++k) dst[m][k] = *(const LAS bf16x8*)(lds + PG8_SA(b, h) + aoff + m * 2048 + k * 1024); } while (0)
; #define PG8_LDB(dst, b, h) do { _Pragma("unroll") for (int n = 0; n < 2; ++n) _Pragma("unroll") for (int k = 0; k < 2; ++k) dst[n][k] = *(const LAS bf16x8*)(lds + PG8_SB(b, h) + boff + n * 2048 + k * 1024); } while (0)
; #define PG8_MMA(ai, bj, At, Bt) do { __builtin_amdgcn_s_setprio(1); _Pragma("unroll") for (int m = 0; m < 4; ++m) _Pragma("unroll") for (int n = 0; n < 2; ++n) _Pragma("unroll") for (int k = 0; k < 2; ++k) \
;         acc[ai][bj][m][n] = __builtin_amdgcn_mfma_f32_16x16x32_bf16(Bt[n][k], At[m][k], acc[ai][bj][m][n], 0, 0, 0); __builtin_amdgcn_s_setprio(0); } while (0)
; #define PG8_WAIT_L(n) asm volatile("s_waitcnt lgkmcnt(" #n ")" ::: "memory")
; #define PG8_BAR __builtin_amdgcn_s_barrier()
; #define PG8_SCHED __builtin_amdgcn_sched_barrier(0)
; template <class Epi, bool SEG>
; __device__ __forceinline__ void gemm_phase(LAS unsigned char* lds, const Gemm g, const StaticOrder& S, const Epi& E) {
;     ...
;         for (int t = 0; t < nt; t += 2) {
;             const bool last = (t == nt - 2);
;             const char* a1 = cA + akoff<SEG>(t) + kstep;
;             const char* a2 = last ? nA : cA + akoff<SEG>(t + 2); const char* b2 = last ? nB : cB + (size_t)(t + 2) * kstep;
;             const char* a3 = a2 + kstep; const char* b3 = b2 + kstep;
;             PG8_LDB(B0, 0, 0); PG8_SCHED; PG8_LDA(At, 0, 0); PG8_STAGE(PG8_SA(1, 1), a1 + hstepA, voffA);
;             PG8_WAIT_L(8); PG8_BAR; PG8_WAIT_L(0); PG8_MMA(0, 0, At, B0); PG8_BAR; PG8_SCHED;
;             PG8_LDB(B1, 0, 1); PG8_STAGE(PG8_SB(0, 0), b2, voffB);
;             PG8_BAR; PG8_WAIT_L(0); PG8_MMA(0, 1, At, B1); PG8_BAR;
;             PG8_LDA(At, 0, 1); PG8_STAGE(PG8_SA(0, 0), a2, voffA);
;             PG8_BAR; PG8_WAIT_L(0); PG8_MMA(1, 0, At, B0); PG8_BAR; PG8_SCHED;
.LBB0_517:
	s_add_u32 s14, s12, 0xfff80080
	s_addc_u32 s15, s13, -1
	s_add_i32 s37, 0, 0x10000
	v_add_u32_e32 v179, s37, v157
	ds_read_b128 v[152:155], v179
	ds_read_b128 v[180:183], v179 offset:1024
	ds_read_b128 v[184:187], v179 offset:2048
	ds_read_b128 v[188:191], v179 offset:3072
	s_cmp_eq_u32 s36, 28
	s_cselect_b32 s17, s5, s15
	s_cselect_b32 s16, s30, s14
	s_cselect_b32 s15, s1, s35
	s_cselect_b32 s14, s31, s34
	v_lshl_add_u64 v[192:193], s[12:13], 0, v[148:149]
	s_add_i32 m0, s11, 0xc000
	ds_read_b128 v[198:201], v159
	ds_read_b128 v[202:205], v159 offset:1024
	ds_read_b128 v[206:209], v159 offset:2048
	ds_read_b128 v[210:213], v159 offset:3072
	ds_read_b128 v[214:217], v159 offset:4096
	ds_read_b128 v[218:221], v159 offset:5120
	ds_read_b128 v[222:225], v159 offset:6144
	ds_read_b128 v[226:229], v159 offset:7168
	global_load_lds_dwordx4 v[192:193], off
	v_lshl_add_u64 v[192:193], s[12:13], 0, v[150:151]
	s_add_i32 m0, s11, 0xe000
	s_nop 0
	global_load_lds_dwordx4 v[192:193], off
	s_waitcnt lgkmcnt(8)
	s_barrier
	s_waitcnt lgkmcnt(0)
	v_mfma_f32_16x16x32_bf16 v[126:129], v[152:155], v[198:201], v[126:129]
	v_mfma_f32_16x16x32_bf16 v[122:125], v[184:187], v[198:201], v[122:125]
	v_mfma_f32_16x16x32_bf16 v[118:121], v[152:155], v[206:209], v[118:121]
	v_mfma_f32_16x16x32_bf16 v[110:113], v[184:187], v[206:209], v[110:113]
	v_mfma_f32_16x16x32_bf16 v[102:105], v[152:155], v[214:217], v[102:105]
	v_mfma_f32_16x16x32_bf16 v[94:97], v[184:187], v[214:217], v[94:97]
	v_mfma_f32_16x16x32_bf16 v[86:89], v[152:155], v[222:225], v[86:89]
	v_mfma_f32_16x16x32_bf16 v[78:81], v[184:187], v[222:225], v[78:81]
	v_mfma_f32_16x16x32_bf16 v[126:129], v[180:183], v[202:205], v[126:129]
	v_mfma_f32_16x16x32_bf16 v[122:125], v[188:191], v[202:205], v[122:125]
	v_mfma_f32_16x16x32_bf16 v[118:121], v[180:183], v[210:213], v[118:121]
	v_mfma_f32_16x16x32_bf16 v[110:113], v[188:191], v[210:213], v[110:113]
	v_mfma_f32_16x16x32_bf16 v[102:105], v[180:183], v[218:221], v[102:105]
	v_mfma_f32_16x16x32_bf16 v[94:97], v[188:191], v[218:221], v[94:97]
	v_mfma_f32_16x16x32_bf16 v[86:89], v[180:183], v[226:229], v[86:89]
	v_mfma_f32_16x16x32_bf16 v[78:81], v[188:191], v[226:229], v[78:81]
	s_barrier
	s_add_i32 s40, 0, 0x14000
	s_add_i32 s37, s37, s20
	v_add_u32_e32 v179, s40, v157
	v_lshl_add_u64 v[192:193], s[14:15], 0, v[0:1]
	s_mov_b32 m0, s37
	ds_read_b128 v[230:233], v179
	ds_read_b128 v[234:237], v179 offset:1024
	ds_read_b128 v[238:241], v179 offset:2048
	ds_read_b128 v[242:245], v179 offset:3072
	global_load_lds_dwordx4 v[192:193], off
	v_lshl_add_u64 v[246:247], s[14:15], 0, v[142:143]
	s_add_i32 m0, s37, 0x2000
	s_nop 0
	global_load_lds_dwordx4 v[246:247], off
	s_barrier
	s_waitcnt lgkmcnt(0)
	v_mfma_f32_16x16x32_bf16 v[114:117], v[230:233], v[198:201], v[114:117]
	v_mfma_f32_16x16x32_bf16 v[106:109], v[238:241], v[198:201], v[106:109]
	v_mfma_f32_16x16x32_bf16 v[98:101], v[230:233], v[206:209], v[98:101]
	v_mfma_f32_16x16x32_bf16 v[90:93], v[238:241], v[206:209], v[90:93]
	v_mfma_f32_16x16x32_bf16 v[82:85], v[230:233], v[214:217], v[82:85]
	v_mfma_f32_16x16x32_bf16 v[74:77], v[238:241], v[214:217], v[74:77]
	v_mfma_f32_16x16x32_bf16 v[70:73], v[230:233], v[222:225], v[70:73]
	v_mfma_f32_16x16x32_bf16 v[66:69], v[238:241], v[222:225], v[66:69]
	v_mfma_f32_16x16x32_bf16 v[114:117], v[234:237], v[202:205], v[114:117]
	v_mfma_f32_16x16x32_bf16 v[106:109], v[242:245], v[202:205], v[106:109]
	v_mfma_f32_16x16x32_bf16 v[98:101], v[234:237], v[210:213], v[98:101]
	v_mfma_f32_16x16x32_bf16 v[90:93], v[242:245], v[210:213], v[90:93]
	v_mfma_f32_16x16x32_bf16 v[82:85], v[234:237], v[218:221], v[82:85]
	v_mfma_f32_16x16x32_bf16 v[74:77], v[242:245], v[218:221], v[74:77]
	v_mfma_f32_16x16x32_bf16 v[70:73], v[234:237], v[226:229], v[70:73]
	v_mfma_f32_16x16x32_bf16 v[66:69], v[242:245], v[226:229], v[66:69]
	s_mov_b32 m0, s11
	v_lshl_add_u64 v[248:249], s[16:17], 0, v[146:147]
	s_barrier
	ds_read_b128 v[198:201], v159 offset:16384
	ds_read_b128 v[202:205], v159 offset:17408
	ds_read_b128 v[206:209], v159 offset:18432
	ds_read_b128 v[210:213], v159 offset:19456
	ds_read_b128 v[214:217], v159 offset:20480
	ds_read_b128 v[218:221], v159 offset:21504
	ds_read_b128 v[222:225], v159 offset:22528
	ds_read_b128 v[226:229], v159 offset:23552
	global_load_lds_dwordx4 v[248:249], off
	v_lshl_add_u64 v[250:251], s[16:17], 0, v[144:145]
	s_mov_b32 m0, s23
	s_nop 0
	global_load_lds_dwordx4 v[250:251], off
	s_barrier
	s_waitcnt lgkmcnt(0)
	v_mfma_f32_16x16x32_bf16 v[62:65], v[152:155], v[198:201], v[62:65]
	v_mfma_f32_16x16x32_bf16 v[58:61], v[184:187], v[198:201], v[58:61]
	v_mfma_f32_16x16x32_bf16 v[54:57], v[152:155], v[206:209], v[54:57]
	v_mfma_f32_16x16x32_bf16 v[46:49], v[184:187], v[206:209], v[46:49]
	v_mfma_f32_16x16x32_bf16 v[38:41], v[152:155], v[214:217], v[38:41]
	v_mfma_f32_16x16x32_bf16 v[30:33], v[184:187], v[214:217], v[30:33]
	v_mfma_f32_16x16x32_bf16 v[22:25], v[152:155], v[222:225], v[22:25]
	v_mfma_f32_16x16x32_bf16 v[14:17], v[184:187], v[222:225], v[14:17]
	v_mfma_f32_16x16x32_bf16 v[62:65], v[180:183], v[202:205], v[62:65]
	v_mfma_f32_16x16x32_bf16 v[58:61], v[188:191], v[202:205], v[58:61]
	v_mfma_f32_16x16x32_bf16 v[54:57], v[180:183], v[210:213], v[54:57]
	v_mfma_f32_16x16x32_bf16 v[46:49], v[188:191], v[210:213], v[46:49]
	v_mfma_f32_16x16x32_bf16 v[38:41], v[180:183], v[218:221], v[38:41]
	v_mfma_f32_16x16x32_bf16 v[30:33], v[188:191], v[218:221], v[30:33]
	v_mfma_f32_16x16x32_bf16 v[22:25], v[180:183], v[226:229], v[22:25]
	v_mfma_f32_16x16x32_bf16 v[14:17], v[188:191], v[226:229], v[14:17]
	s_barrier
; #define PG8_STAGE(bufoff, gbase, voff) do { _Pragma("unroll") for (int _i = 0; _i < 2; ++_i) \
;         __builtin_amdgcn_global_load_lds((const unsigned*)((const char*)(gbase) + (voff)[_i]), (LAS unsigned*)(lds + (bufoff) + ldsw + _i * 8192), 16, 0, 0); } while (0)
; #define PG8_LDA(dst, b, h) do { _Pragma("unroll") for (int m = 0; m < 4; ++m) _Pragma("unroll") for (int k = 0; k < 2; ++k) dst[m][k] = *(const LAS bf16x8*)(lds + PG8_SA(b, h) + aoff + m * 2048 + k * 1024); } while (0)
; #define PG8_LDB(dst, b, h) do { _Pragma("unroll") for (int n = 0; n < 2; ++n) _Pragma("unroll") for (int k = 0; k < 2; ++k) dst[n][k] = *(const LAS bf16x8*)(lds + PG8_SB(b, h) + boff + n * 2048 + k * 1024); } while (0)
; #define PG8_MMA(ai, bj, At, Bt) do { __builtin_amdgcn_s_setprio(1); _Pragma("unroll") for (int m = 0; m < 4; ++m) _Pragma("unroll") for (int n = 0; n < 2; ++n) _Pragma("unroll") for (int k = 0; k < 2; ++k) \
;         acc[ai][bj][m][n] = __builtin_amdgcn_mfma_f32_16x16x32_bf16(Bt[n][k], At[m][k], acc[ai][bj][m][n], 0, 0, 0); __builtin_amdgcn_s_setprio(0); } while (0)
; #define PG8_WAIT_V(n) asm volatile("s_waitcnt vmcnt(" #n ")" ::: "memory")
; #define PG8_WAIT_L(n) asm volatile("s_waitcnt lgkmcnt(" #n ")" ::: "memory")
; #define PG8_BAR __builtin_amdgcn_s_barrier()
; #define PG8_SCHED __builtin_amdgcn_sched_barrier(0)
; template <class Epi, bool SEG>
; __device__ __forceinline__ void gemm_phase(LAS unsigned char* lds, const Gemm g, const StaticOrder& S, const Epi& E) {
;     ...
;             PG8_STAGE(PG8_SB(0, 1), b2 + hstepB, voffB);
;             PG8_WAIT_V(6); PG8_BAR; PG8_MMA(1, 1, At, B1); PG8_BAR;
;             PG8_LDB(B0, 1, 0); PG8_SCHED; PG8_LDA(At, 1, 0); PG8_STAGE(PG8_SA(0, 1), a2 + hstepA, voffA);
;             PG8_WAIT_L(8); PG8_BAR; PG8_WAIT_L(0); PG8_MMA(0, 0, At, B0); PG8_BAR; PG8_SCHED;
;             PG8_LDB(B1, 1, 1); PG8_STAGE(PG8_SB(1, 0), b3, voffB);
;             PG8_BAR; PG8_WAIT_L(0); PG8_MMA(0, 1, At, B1); PG8_BAR;
;             PG8_LDA(At, 1, 1); PG8_STAGE(PG8_SA(1, 0), a3, voffA);
	s_add_u32 s38, s14, 0x80000
	s_addc_u32 s39, s15, 0
	s_add_i32 s37, s40, s20
	v_lshl_add_u64 v[152:153], s[38:39], 0, v[0:1]
	s_mov_b32 m0, s37
	s_nop 0
	global_load_lds_dwordx4 v[152:153], off
	v_lshl_add_u64 v[152:153], s[38:39], 0, v[142:143]
	s_add_i32 m0, s37, 0x2000
	s_nop 0
	global_load_lds_dwordx4 v[152:153], off
	s_waitcnt vmcnt(6)
	s_barrier
	v_mfma_f32_16x16x32_bf16 v[50:53], v[230:233], v[198:201], v[50:53]
	v_mfma_f32_16x16x32_bf16 v[42:45], v[238:241], v[198:201], v[42:45]
	v_mfma_f32_16x16x32_bf16 v[34:37], v[230:233], v[206:209], v[34:37]
	v_mfma_f32_16x16x32_bf16 v[26:29], v[238:241], v[206:209], v[26:29]
	v_mfma_f32_16x16x32_bf16 v[18:21], v[230:233], v[214:217], v[18:21]
	v_mfma_f32_16x16x32_bf16 v[10:13], v[238:241], v[214:217], v[10:13]
	v_mfma_f32_16x16x32_bf16 v[6:9], v[230:233], v[222:225], v[6:9]
	v_mfma_f32_16x16x32_bf16 v[2:5], v[238:241], v[222:225], v[2:5]
	v_mfma_f32_16x16x32_bf16 v[50:53], v[234:237], v[202:205], v[50:53]
	v_mfma_f32_16x16x32_bf16 v[42:45], v[242:245], v[202:205], v[42:45]
	v_mfma_f32_16x16x32_bf16 v[34:37], v[234:237], v[210:213], v[34:37]
	v_mfma_f32_16x16x32_bf16 v[26:29], v[242:245], v[210:213], v[26:29]
	v_mfma_f32_16x16x32_bf16 v[18:21], v[234:237], v[218:221], v[18:21]
	v_mfma_f32_16x16x32_bf16 v[10:13], v[242:245], v[218:221], v[10:13]
	v_mfma_f32_16x16x32_bf16 v[6:9], v[234:237], v[226:229], v[6:9]
	v_mfma_f32_16x16x32_bf16 v[2:5], v[242:245], v[226:229], v[2:5]
	s_add_i32 s37, 0, 0x18000
	v_add_u32_e32 v179, s37, v157
	s_barrier
	ds_read_b128 v[152:155], v179
	ds_read_b128 v[180:183], v179 offset:1024
	ds_read_b128 v[184:187], v179 offset:2048
	ds_read_b128 v[188:191], v179 offset:3072
	s_add_u32 s16, s16, 0x80000
	s_addc_u32 s17, s17, 0
	s_mov_b32 m0, s24
	v_lshl_add_u64 v[230:231], s[16:17], 0, v[146:147]
	ds_read_b128 v[198:201], v159 offset:32768
	ds_read_b128 v[202:205], v159 offset:33792
	ds_read_b128 v[206:209], v159 offset:34816
	ds_read_b128 v[210:213], v159 offset:35840
	ds_read_b128 v[214:217], v159 offset:36864
	ds_read_b128 v[218:221], v159 offset:37888
	ds_read_b128 v[222:225], v159 offset:38912
	ds_read_b128 v[226:229], v159 offset:39936
	global_load_lds_dwordx4 v[230:231], off
	v_lshl_add_u64 v[230:231], s[16:17], 0, v[144:145]
	s_mov_b32 m0, s25
	s_nop 0
	global_load_lds_dwordx4 v[230:231], off
	s_waitcnt lgkmcnt(8)
	s_barrier
	s_waitcnt lgkmcnt(0)
	v_mfma_f32_16x16x32_bf16 v[126:129], v[152:155], v[198:201], v[126:129]
	v_mfma_f32_16x16x32_bf16 v[122:125], v[184:187], v[198:201], v[122:125]
	v_mfma_f32_16x16x32_bf16 v[118:121], v[152:155], v[206:209], v[118:121]
	v_mfma_f32_16x16x32_bf16 v[110:113], v[184:187], v[206:209], v[110:113]
	v_mfma_f32_16x16x32_bf16 v[102:105], v[152:155], v[214:217], v[102:105]
	v_mfma_f32_16x16x32_bf16 v[94:97], v[184:187], v[214:217], v[94:97]
	v_mfma_f32_16x16x32_bf16 v[86:89], v[152:155], v[222:225], v[86:89]
	v_mfma_f32_16x16x32_bf16 v[78:81], v[184:187], v[222:225], v[78:81]
	v_mfma_f32_16x16x32_bf16 v[126:129], v[180:183], v[202:205], v[126:129]
	v_mfma_f32_16x16x32_bf16 v[122:125], v[188:191], v[202:205], v[122:125]
	v_mfma_f32_16x16x32_bf16 v[118:121], v[180:183], v[210:213], v[118:121]
	v_mfma_f32_16x16x32_bf16 v[110:113], v[188:191], v[210:213], v[110:113]
	v_mfma_f32_16x16x32_bf16 v[102:105], v[180:183], v[218:221], v[102:105]
	v_mfma_f32_16x16x32_bf16 v[94:97], v[188:191], v[218:221], v[94:97]
	v_mfma_f32_16x16x32_bf16 v[86:89], v[180:183], v[226:229], v[86:89]
	v_mfma_f32_16x16x32_bf16 v[78:81], v[188:191], v[226:229], v[78:81]
	s_barrier
	s_add_i32 s16, 0, 0x1c000
	s_add_i32 s17, s37, s20
	v_add_u32_e32 v179, s16, v157
	v_lshl_add_u64 v[192:193], v[192:193], 0, s[96:97]
	s_mov_b32 m0, s17
	ds_read_b128 v[230:233], v179
	ds_read_b128 v[234:237], v179 offset:1024
	ds_read_b128 v[238:241], v179 offset:2048
	ds_read_b128 v[242:245], v179 offset:3072
	global_load_lds_dwordx4 v[192:193], off
	v_lshl_add_u64 v[192:193], v[246:247], 0, s[96:97]
	s_add_i32 m0, s17, 0x2000
	s_nop 0
	global_load_lds_dwordx4 v[192:193], off
	s_barrier
	s_waitcnt lgkmcnt(0)
	v_mfma_f32_16x16x32_bf16 v[114:117], v[230:233], v[198:201], v[114:117]
	v_mfma_f32_16x16x32_bf16 v[106:109], v[238:241], v[198:201], v[106:109]
	v_mfma_f32_16x16x32_bf16 v[98:101], v[230:233], v[206:209], v[98:101]
	v_mfma_f32_16x16x32_bf16 v[90:93], v[238:241], v[206:209], v[90:93]
	v_mfma_f32_16x16x32_bf16 v[82:85], v[230:233], v[214:217], v[82:85]
	v_mfma_f32_16x16x32_bf16 v[74:77], v[238:241], v[214:217], v[74:77]
	v_mfma_f32_16x16x32_bf16 v[70:73], v[230:233], v[222:225], v[70:73]
	v_mfma_f32_16x16x32_bf16 v[66:69], v[238:241], v[222:225], v[66:69]
	v_mfma_f32_16x16x32_bf16 v[114:117], v[234:237], v[202:205], v[114:117]
	v_mfma_f32_16x16x32_bf16 v[106:109], v[242:245], v[202:205], v[106:109]
	v_mfma_f32_16x16x32_bf16 v[98:101], v[234:237], v[210:213], v[98:101]
	v_mfma_f32_16x16x32_bf16 v[90:93], v[242:245], v[210:213], v[90:93]
	v_mfma_f32_16x16x32_bf16 v[82:85], v[234:237], v[218:221], v[82:85]
	v_mfma_f32_16x16x32_bf16 v[74:77], v[242:245], v[218:221], v[74:77]
	v_mfma_f32_16x16x32_bf16 v[70:73], v[234:237], v[226:229], v[70:73]
	v_mfma_f32_16x16x32_bf16 v[66:69], v[242:245], v[226:229], v[66:69]
	s_mov_b32 m0, s26
	v_lshl_add_u64 v[192:193], v[248:249], 0, s[96:97]
	s_barrier
	ds_read_b128 v[198:201], v159 offset:49152
	ds_read_b128 v[202:205], v159 offset:50176
	ds_read_b128 v[206:209], v159 offset:51200
	ds_read_b128 v[210:213], v159 offset:52224
	ds_read_b128 v[214:217], v159 offset:53248
	ds_read_b128 v[218:221], v159 offset:54272
	ds_read_b128 v[222:225], v159 offset:55296
	ds_read_b128 v[226:229], v159 offset:56320
	global_load_lds_dwordx4 v[192:193], off
	v_lshl_add_u64 v[192:193], v[250:251], 0, s[96:97]
	s_mov_b32 m0, s27
	s_nop 0
	global_load_lds_dwordx4 v[192:193], off
	s_barrier
; #define PG8_STAGE(bufoff, gbase, voff) do { _Pragma("unroll") for (int _i = 0; _i < 2; ++_i) \
;         __builtin_amdgcn_global_load_lds((const unsigned*)((const char*)(gbase) + (voff)[_i]), (LAS unsigned*)(lds + (bufoff) + ldsw + _i * 8192), 16, 0, 0); } while (0)
; #define PG8_MMA(ai, bj, At, Bt) do { __builtin_amdgcn_s_setprio(1); _Pragma("unroll") for (int m = 0; m < 4; ++m) _Pragma("unroll") for (int n = 0; n < 2; ++n) _Pragma("unroll") for (int k = 0; k < 2; ++k) \
;         acc[ai][bj][m][n] = __builtin_amdgcn_mfma_f32_16x16x32_bf16(Bt[n][k], At[m][k], acc[ai][bj][m][n], 0, 0, 0); __builtin_amdgcn_s_setprio(0); } while (0)
; #define PG8_WAIT_V(n) asm volatile("s_waitcnt vmcnt(" #n ")" ::: "memory")
; #define PG8_WAIT_L(n) asm volatile("s_waitcnt lgkmcnt(" #n ")" ::: "memory")
; #define PG8_BAR __builtin_amdgcn_s_barrier()
; #define PG8_SCHED __builtin_amdgcn_sched_barrier(0)
; template <class Epi, bool SEG>
; __device__ __forceinline__ void gemm_phase(LAS unsigned char* lds, const Gemm g, const StaticOrder& S, const Epi& E) {
;     ...
;             PG8_BAR; PG8_WAIT_L(0); PG8_MMA(1, 0, At, B0); PG8_BAR; PG8_SCHED;
;             PG8_STAGE(PG8_SB(1, 1), b3 + hstepB, voffB);
;             PG8_WAIT_V(6); PG8_BAR; PG8_MMA(1, 1, At, B1); PG8_BAR;
;         }
	s_waitcnt lgkmcnt(0)
	v_mfma_f32_16x16x32_bf16 v[62:65], v[152:155], v[198:201], v[62:65]
	v_mfma_f32_16x16x32_bf16 v[58:61], v[184:187], v[198:201], v[58:61]
	v_mfma_f32_16x16x32_bf16 v[54:57], v[152:155], v[206:209], v[54:57]
	v_mfma_f32_16x16x32_bf16 v[46:49], v[184:187], v[206:209], v[46:49]
	v_mfma_f32_16x16x32_bf16 v[38:41], v[152:155], v[214:217], v[38:41]
	v_mfma_f32_16x16x32_bf16 v[30:33], v[184:187], v[214:217], v[30:33]
	v_mfma_f32_16x16x32_bf16 v[22:25], v[152:155], v[222:225], v[22:25]
	v_mfma_f32_16x16x32_bf16 v[14:17], v[184:187], v[222:225], v[14:17]
	v_mfma_f32_16x16x32_bf16 v[62:65], v[180:183], v[202:205], v[62:65]
	v_mfma_f32_16x16x32_bf16 v[58:61], v[188:191], v[202:205], v[58:61]
	v_mfma_f32_16x16x32_bf16 v[54:57], v[180:183], v[210:213], v[54:57]
	v_mfma_f32_16x16x32_bf16 v[46:49], v[188:191], v[210:213], v[46:49]
	v_mfma_f32_16x16x32_bf16 v[38:41], v[180:183], v[218:221], v[38:41]
	v_mfma_f32_16x16x32_bf16 v[30:33], v[188:191], v[218:221], v[30:33]
	v_mfma_f32_16x16x32_bf16 v[22:25], v[180:183], v[226:229], v[22:25]
	v_mfma_f32_16x16x32_bf16 v[14:17], v[188:191], v[226:229], v[14:17]
	s_barrier
	s_add_u32 s14, s14, 0x80080
	s_addc_u32 s15, s15, 0
	s_add_i32 s16, s16, s20
	v_lshl_add_u64 v[152:153], s[14:15], 0, v[0:1]
	s_mov_b32 m0, s16
	s_nop 0
	global_load_lds_dwordx4 v[152:153], off
	v_lshl_add_u64 v[152:153], s[14:15], 0, v[142:143]
	s_add_i32 m0, s16, 0x2000
	s_nop 0
	global_load_lds_dwordx4 v[152:153], off
	s_waitcnt vmcnt(6)
	s_barrier
	v_mfma_f32_16x16x32_bf16 v[50:53], v[230:233], v[198:201], v[50:53]
	v_mfma_f32_16x16x32_bf16 v[42:45], v[238:241], v[198:201], v[42:45]
	v_mfma_f32_16x16x32_bf16 v[34:37], v[230:233], v[206:209], v[34:37]
	v_mfma_f32_16x16x32_bf16 v[26:29], v[238:241], v[206:209], v[26:29]
	v_mfma_f32_16x16x32_bf16 v[18:21], v[230:233], v[214:217], v[18:21]
	v_mfma_f32_16x16x32_bf16 v[10:13], v[238:241], v[214:217], v[10:13]
	v_mfma_f32_16x16x32_bf16 v[6:9], v[230:233], v[222:225], v[6:9]
	v_mfma_f32_16x16x32_bf16 v[2:5], v[238:241], v[222:225], v[2:5]
	v_mfma_f32_16x16x32_bf16 v[50:53], v[234:237], v[202:205], v[50:53]
	v_mfma_f32_16x16x32_bf16 v[42:45], v[242:245], v[202:205], v[42:45]
	v_mfma_f32_16x16x32_bf16 v[34:37], v[234:237], v[210:213], v[34:37]
	v_mfma_f32_16x16x32_bf16 v[26:29], v[242:245], v[210:213], v[26:29]
	v_mfma_f32_16x16x32_bf16 v[18:21], v[234:237], v[218:221], v[18:21]
	v_mfma_f32_16x16x32_bf16 v[10:13], v[242:245], v[218:221], v[10:13]
	v_mfma_f32_16x16x32_bf16 v[6:9], v[234:237], v[226:229], v[6:9]
	v_mfma_f32_16x16x32_bf16 v[2:5], v[242:245], v[226:229], v[2:5]
	s_add_i32 s36, s36, 2
	s_add_u32 s12, s12, 0x100
	s_addc_u32 s13, s13, 0
	s_add_u32 s34, s34, 0x100
	s_addc_u32 s35, s35, 0
	s_cmp_gt_u32 s36, 29
	s_barrier
	s_cbranch_scc0 .LBB0_517
; __device__ __forceinline__ unsigned cvt_pk_bf16(float lo, float hi) { unsigned r; asm("v_cvt_pk_bf16_f32 %0, %1, %2" : "=v"(r) : "v"(lo), "v"(hi)); return r; }
; #define PG8_WAIT_V(n) asm volatile("s_waitcnt vmcnt(" #n ")" ::: "memory")
; #define PG8_BAR __builtin_amdgcn_s_barrier()
;     __device__ __forceinline__ void operator()(const f32x4 (&acc)[2][2][4][2], const Unit& u, int wr, int wc, int fr, int fq) const {
;         const int row0 = u.pm * BM + wr * 64 + fr, col0 = u.pn * BM + wc * 32 + 8 * fq;
; #pragma unroll
;         for (int ai = 0; ai < 2; ++ai)
; #pragma unroll
;             for (int m = 0; m < 4; ++m) { bf16_t* rowp = O + (size_t)(row0 + ai * HALF + m * 16) * ldc + col0;
; #pragma unroll
;                 for (int bj = 0; bj < 2; ++bj) { f32x4 v0 = acc[ai][bj][m][0], v1 = acc[ai][bj][m][1];
;                     if (ACT == 1) {
; #pragma unroll
;                         for (int j = 0; j < 4; ++j) { const float a = fmaxf(v0[j], 0.f), b = fmaxf(v1[j], 0.f); v0[j] = a * a; v1[j] = b * b; } }
;                     u32x4 w; w.x = cvt_pk_bf16(v0[0], v0[1]); w.y = cvt_pk_bf16(v0[2], v0[3]); w.z = cvt_pk_bf16(v1[0], v1[1]); w.w = cvt_pk_bf16(v1[2], v1[3]);
;                     *(u32x4*)(rowp + bj * HALF) = w; } }
; template <class Epi, bool SEG>
; __device__ __forceinline__ void gemm_phase(LAS unsigned char* lds, const Gemm g, const StaticOrder& S, const Epi& E) {
;     ...
;         E(acc, cur, wr, wc, fr, fq);
;         if (!has_next) break;
; #pragma unroll
;         for (int a = 0; a < 2; ++a)
; #pragma unroll
;             for (int b = 0; b < 2; ++b)
; #pragma unroll
;                 for (int m = 0; m < 4; ++m)
; #pragma unroll
;                     for (int n = 0; n < 2; ++n) acc[a][b][m][n] = (f32x4){0.f, 0.f, 0.f, 0.f};
;         cur = nxt; cA = nA; cB = nB; ++ui;
;     }
;     PG8_WAIT_V(0);
;     if (wr == 0) PG8_BAR;
;     PG8_BAR;
	v_lshl_add_u32 v179, s10, 8, v156
	v_lshl_or_b32 v154, s29, 8, v158
	v_ashrrev_i32_e32 v155, 31, v154
	v_mov_b64_e32 v[152:153], s[78:79]
	v_cvt_pk_bf16_f32 v70, v70, v71
	v_cvt_pk_bf16_f32 v71, v72, v73
	v_cvt_pk_bf16_f32 v72, v66, v67
	v_add_u32_e32 v66, 0x80, v179
	v_mad_i64_i32 v[180:181], s[12:13], v179, s22, v[152:153]
	v_lshlrev_b64 v[154:155], 1, v[154:155]
	v_cvt_pk_bf16_f32 v114, v114, v115
	v_cvt_pk_bf16_f32 v115, v116, v117
	v_cvt_pk_bf16_f32 v116, v106, v107
	v_or_b32_e32 v106, 16, v179
	v_mad_i64_i32 v[66:67], s[12:13], v66, s22, v[152:153]
	v_cvt_pk_bf16_f32 v50, v50, v51
	v_cvt_pk_bf16_f32 v51, v52, v53
	v_cvt_pk_bf16_f32 v52, v42, v43
	v_add_u32_e32 v42, 0x90, v179
	v_lshl_add_u64 v[180:181], v[180:181], 0, v[154:155]
	v_mad_i64_i32 v[106:107], s[12:13], v106, s22, v[152:153]
	v_cvt_pk_bf16_f32 v98, v98, v99
	v_cvt_pk_bf16_f32 v99, v100, v101
	v_cvt_pk_bf16_f32 v100, v90, v91
	v_or_b32_e32 v90, 32, v179
	v_lshl_add_u64 v[66:67], v[66:67], 0, v[154:155]
	v_mad_i64_i32 v[42:43], s[12:13], v42, s22, v[152:153]
	v_cvt_pk_bf16_f32 v34, v34, v35
	v_cvt_pk_bf16_f32 v35, v36, v37
	v_cvt_pk_bf16_f32 v36, v26, v27
	v_add_u32_e32 v26, 0xa0, v179
	v_cvt_pk_bf16_f32 v117, v108, v109
	global_store_dwordx4 v[180:181], v[114:117], off offset:256
	v_mad_i64_i32 v[90:91], s[12:13], v90, s22, v[152:153]
	s_nop 0
	v_lshl_add_u64 v[114:115], v[106:107], 0, v[154:155]
	v_cvt_pk_bf16_f32 v82, v82, v83
	v_cvt_pk_bf16_f32 v83, v84, v85
	v_cvt_pk_bf16_f32 v84, v74, v75
	v_or_b32_e32 v74, 48, v179
	v_cvt_pk_bf16_f32 v53, v44, v45
	global_store_dwordx4 v[66:67], v[50:53], off offset:256
	v_mad_i64_i32 v[26:27], s[12:13], v26, s22, v[152:153]
	s_nop 0
	v_lshl_add_u64 v[50:51], v[42:43], 0, v[154:155]
	v_cvt_pk_bf16_f32 v18, v18, v19
	v_cvt_pk_bf16_f32 v19, v20, v21
	v_cvt_pk_bf16_f32 v20, v10, v11
	v_add_u32_e32 v10, 0xb0, v179
	v_cvt_pk_bf16_f32 v101, v92, v93
	global_store_dwordx4 v[114:115], v[98:101], off offset:256
	v_mad_i64_i32 v[74:75], s[12:13], v74, s22, v[152:153]
	s_nop 0
	v_lshl_add_u64 v[98:99], v[90:91], 0, v[154:155]
	v_cvt_pk_bf16_f32 v37, v28, v29
	global_store_dwordx4 v[50:51], v[34:37], off offset:256
	v_mad_i64_i32 v[10:11], s[12:13], v10, s22, v[152:153]
	s_nop 0
	v_lshl_add_u64 v[34:35], v[26:27], 0, v[154:155]
	v_cvt_pk_bf16_f32 v85, v76, v77
	global_store_dwordx4 v[98:99], v[82:85], off offset:256
	v_cvt_pk_bf16_f32 v21, v12, v13
	global_store_dwordx4 v[34:35], v[18:21], off offset:256
	s_and_b64 vcc, exec, s[2:3]
	v_lshl_add_u64 v[82:83], v[74:75], 0, v[154:155]
	v_lshl_add_u64 v[18:19], v[10:11], 0, v[154:155]
	s_mov_b32 s29, s0
	s_mov_b32 s10, s4
	s_mov_b64 s[14:15], s[8:9]
	s_mov_b64 s[12:13], s[6:7]
	v_cvt_pk_bf16_f32 v126, v126, v127
	v_cvt_pk_bf16_f32 v127, v128, v129
	v_cvt_pk_bf16_f32 v128, v122, v123
	v_cvt_pk_bf16_f32 v129, v124, v125
	global_store_dwordx4 v[180:181], v[126:129], off
	v_cvt_pk_bf16_f32 v106, v118, v119
	v_cvt_pk_bf16_f32 v107, v120, v121
	v_cvt_pk_bf16_f32 v108, v110, v111
	v_cvt_pk_bf16_f32 v109, v112, v113
	global_store_dwordx4 v[114:115], v[106:109], off
	v_cvt_pk_bf16_f32 v90, v102, v103
	v_cvt_pk_bf16_f32 v91, v104, v105
	v_cvt_pk_bf16_f32 v92, v94, v95
	v_cvt_pk_bf16_f32 v93, v96, v97
	global_store_dwordx4 v[98:99], v[90:93], off
	v_cvt_pk_bf16_f32 v74, v86, v87
	v_cvt_pk_bf16_f32 v75, v88, v89
	v_cvt_pk_bf16_f32 v76, v78, v79
	v_cvt_pk_bf16_f32 v77, v80, v81
	global_store_dwordx4 v[82:83], v[74:77], off
	v_cvt_pk_bf16_f32 v73, v68, v69
	global_store_dwordx4 v[82:83], v[70:73], off offset:256
	v_cvt_pk_bf16_f32 v62, v62, v63
	v_cvt_pk_bf16_f32 v63, v64, v65
	v_cvt_pk_bf16_f32 v64, v58, v59
	v_cvt_pk_bf16_f32 v65, v60, v61
	global_store_dwordx4 v[66:67], v[62:65], off
	v_cvt_pk_bf16_f32 v42, v54, v55
	v_cvt_pk_bf16_f32 v43, v56, v57
	v_cvt_pk_bf16_f32 v44, v46, v47
	v_cvt_pk_bf16_f32 v45, v48, v49
	global_store_dwordx4 v[50:51], v[42:45], off
	v_cvt_pk_bf16_f32 v26, v38, v39
	v_cvt_pk_bf16_f32 v27, v40, v41
	v_cvt_pk_bf16_f32 v28, v30, v31
	v_cvt_pk_bf16_f32 v29, v32, v33
	global_store_dwordx4 v[34:35], v[26:29], off
	v_cvt_pk_bf16_f32 v10, v22, v23
	v_cvt_pk_bf16_f32 v11, v24, v25
	v_cvt_pk_bf16_f32 v12, v14, v15
	v_cvt_pk_bf16_f32 v13, v16, v17
	global_store_dwordx4 v[18:19], v[10:13], off
	v_cvt_pk_bf16_f32 v6, v6, v7
	v_cvt_pk_bf16_f32 v7, v8, v9
	v_cvt_pk_bf16_f32 v8, v2, v3
	v_cvt_pk_bf16_f32 v9, v4, v5
	global_store_dwordx4 v[18:19], v[6:9], off offset:256
	s_cbranch_vccz .LBB0_514
	s_waitcnt vmcnt(0)
	s_cmpk_gt_u32 s19, 0xff
	v_readlane_b32 s29, v254, 8
	s_cbranch_scc1 .LBB0_521
	s_barrier
